# OUT and IN main GEMM tile K-loops also on the 8-phase ping-pong LDS-DMA schedule (IN uses per-half SGPR source pointers)
# speedup vs baseline: 1.0538x; 1.0060x over previous
.LBB0_40:
	s_ashr_i32 s2, s10, 31
	s_lshr_b32 s2, s2, 27
	s_add_i32 s2, s10, s2
	s_ashr_i32 s17, s2, 5
	s_andn2_b32 s2, s2, 31
	s_sub_i32 s2, s10, s2
	s_ashr_i32 s3, s2, 31
	s_lshr_b32 s3, s3, 29
	s_add_i32 s3, s2, s3
	s_ashr_i32 s3, s3, 3
	s_lshl_b32 s2, s2, 8
	s_lshl_b32 s14, s17, 11
	s_lshl_b32 s18, s3, 11
	s_add_i32 s2, s2, s14
	s_sub_i32 s14, s18, s2
	s_addk_i32 s14, 0x3f00
	s_lshl_b32 s15, s3, 8
	v_add_u32_e32 v2, s14, v180
	v_add_u32_e32 v15, s15, v180
	v_mad_i64_i32 v[48:49], s[2:3], v15, s5, v[164:165]
	v_mad_i64_i32 v[50:51], s[2:3], v2, s5, v[166:167]
	s_mov_b32 s2, 0x58000
	s_nop 0
	v_add_co_u32_e32 v52, vcc, s2, v50
	s_mov_b32 s3, 0xb0000
	s_nop 0
	v_addc_co_u32_e32 v53, vcc, 0, v51, vcc
	v_add_co_u32_e32 v54, vcc, s3, v50
	v_addc_co_u32_e32 v55, vcc, 0, v51, vcc
	v_add_co_u32_e32 v56, vcc, s2, v48
	s_mov_b32 s2, 0x108000
	s_nop 0
	v_addc_co_u32_e32 v57, vcc, 0, v49, vcc
	v_add_co_u32_e32 v58, vcc, s3, v48
	v_addc_co_u32_e32 v59, vcc, 0, v49, vcc
	v_add_co_u32_e32 v60, vcc, s2, v48
	v_addc_co_u32_e32 v61, vcc, 0, v49, vcc
	v_add_co_u32_e32 v62, vcc, s2, v50
	v_addc_co_u32_e32 v63, vcc, 0, v51, vcc
	s_mulk_i32 s17, 0x1800
	s_add_i32 s17, s18, s17
	v_mov_b32_e32 v2, 0
	v_mad_i64_i32 v[176:177], s[18:19], v15, s5, v[172:173]
	v_add_u32_e32 v15, s17, v190
	s_mov_b64 s[2:3], 0
	s_mov_b32 s16, 1
	v_mov_b32_e32 v3, v2
	v_mov_b32_e32 v4, v2
	v_mov_b32_e32 v5, v2
	v_mov_b32_e32 v6, v2
	v_mov_b32_e32 v7, v2
	v_mov_b32_e32 v8, v2
	v_mov_b32_e32 v9, v2
	v_mov_b32_e32 v10, v2
	v_mov_b32_e32 v11, v2
	v_mov_b32_e32 v12, v2
	v_mov_b32_e32 v13, v2
	v_mov_b32_e32 v14, v2
	v_mad_i64_i32 v[178:179], s[18:19], v15, s5, v[174:175]
	v_mov_b32_e32 v15, v2
	v_mov_b32_e32 v48, v2
	v_mov_b32_e32 v49, v2
	v_mov_b32_e32 v50, v2
	v_mov_b32_e32 v51, v2
	v_mov_b32_e32 v52, v2
	v_mov_b32_e32 v53, v2
	v_mov_b32_e32 v54, v2
	v_mov_b32_e32 v55, v2
	v_mov_b32_e32 v56, v2
	v_mov_b32_e32 v57, v2
	v_mov_b32_e32 v58, v2
	v_mov_b32_e32 v59, v2
	v_mov_b32_e32 v60, v2
	v_mov_b32_e32 v61, v2
	v_mov_b32_e32 v62, v2
	v_mov_b32_e32 v63, v2
	v_mov_b32_e32 v64, v2
	v_mov_b32_e32 v65, v2
	v_mov_b32_e32 v66, v2
	v_mov_b32_e32 v67, v2
	v_mov_b32_e32 v16, v2
	v_mov_b32_e32 v17, v2
	v_mov_b32_e32 v34, v2
	v_mov_b32_e32 v35, v2
	v_mov_b32_e32 v36, v2
	v_mov_b32_e32 v37, v2
	v_mov_b32_e32 v38, v2
	v_mov_b32_e32 v39, v2
	v_mov_b32_e32 v40, v2
	v_mov_b32_e32 v41, v2
	v_mov_b32_e32 v42, v2
	v_mov_b32_e32 v43, v2
	v_mov_b32_e32 v44, v2
	v_mov_b32_e32 v45, v2
	v_mov_b32_e32 v46, v2
	v_mov_b32_e32 v47, v2
	v_mov_b32_e32 v18, v2
	v_mov_b32_e32 v19, v2
	v_mov_b32_e32 v20, v2
	v_mov_b32_e32 v21, v2
	v_mov_b32_e32 v22, v2
	v_mov_b32_e32 v23, v2
	v_mov_b32_e32 v24, v2
	v_mov_b32_e32 v25, v2
	v_mov_b32_e32 v26, v2
	v_mov_b32_e32 v27, v2
	v_mov_b32_e32 v28, v2
	v_mov_b32_e32 v29, v2
	v_mov_b32_e32 v30, v2
	v_mov_b32_e32 v31, v2
	v_mov_b32_e32 v32, v2
	v_mov_b32_e32 v33, v2
	v_mov_b32_e32 v68, v2
	v_mov_b32_e32 v69, v2
	v_mov_b32_e32 v70, v2
	v_mov_b32_e32 v71, v2
	v_mov_b32_e32 v72, v2
	v_mov_b32_e32 v73, v2
	v_mov_b32_e32 v74, v2
	v_mov_b32_e32 v75, v2
	v_mov_b32_e32 v76, v2
	v_mov_b32_e32 v77, v2
	v_mov_b32_e32 v78, v2
	v_mov_b32_e32 v79, v2
	v_mov_b32_e32 v80, v2
	v_mov_b32_e32 v81, v2
	v_mov_b32_e32 v98, v2
	v_mov_b32_e32 v99, v2
	v_mov_b32_e32 v100, v2
	v_mov_b32_e32 v101, v2
	v_mov_b32_e32 v102, v2
	v_mov_b32_e32 v103, v2
	v_mov_b32_e32 v104, v2
	v_mov_b32_e32 v105, v2
	v_mov_b32_e32 v106, v2
	v_mov_b32_e32 v107, v2
	v_mov_b32_e32 v108, v2
	v_mov_b32_e32 v109, v2
	v_mov_b32_e32 v110, v2
	v_mov_b32_e32 v111, v2
	v_mov_b32_e32 v112, v2
	v_mov_b32_e32 v113, v2
	v_mov_b32_e32 v82, v2
	v_mov_b32_e32 v83, v2
	v_mov_b32_e32 v84, v2
	v_mov_b32_e32 v85, v2
	v_mov_b32_e32 v86, v2
	v_mov_b32_e32 v87, v2
	v_mov_b32_e32 v88, v2
	v_mov_b32_e32 v89, v2
	v_mov_b32_e32 v90, v2
	v_mov_b32_e32 v91, v2
	v_mov_b32_e32 v92, v2
	v_mov_b32_e32 v93, v2
	v_mov_b32_e32 v94, v2
	v_mov_b32_e32 v95, v2
	v_mov_b32_e32 v96, v2
	v_mov_b32_e32 v97, v2
	v_mov_b32_e32 v114, v2
	v_mov_b32_e32 v115, v2
	v_mov_b32_e32 v116, v2
	v_mov_b32_e32 v117, v2
	v_mov_b32_e32 v118, v2
	v_mov_b32_e32 v119, v2
	v_mov_b32_e32 v120, v2
	v_mov_b32_e32 v121, v2
	v_mov_b32_e32 v122, v2
	v_mov_b32_e32 v123, v2
	v_mov_b32_e32 v124, v2
	v_mov_b32_e32 v125, v2
	v_mov_b32_e32 v126, v2
	v_mov_b32_e32 v127, v2
	v_mov_b32_e32 v128, v2
	v_mov_b32_e32 v129, v2
	s_mov_b32 s4, 0x22c5000
	s_mov_b32 s12, 0x231d000
	s_mov_b32 s13, 0x2375000
	s_waitcnt lgkmcnt(0)
	v_lshrrev_b32_e32 v130, 6, v200
	v_and_b32_e32 v131, 63, v200
	v_readfirstlane_b32 s17, v130
	s_lshr_b32 s4, s17, 2
	s_lshl_b32 s4, s4, 7
	s_and_b32 s19, s17, 3
	s_lshl_b32 s19, s19, 4
	s_add_u32 s4, s4, s19
	s_add_u32 s19, s4, s14
	s_mul_i32 s19, s19, 5632
	s_add_u32 s2, s36, 0x518d800
	s_addc_u32 s3, s37, 0
	s_add_u32 s2, s2, s19
	s_addc_u32 s3, s3, 0
	s_lshl_b32 s4, s4, 7
	s_lshr_b32 s16, s17, 1
	s_lshl_b32 s16, s16, 6
	s_and_b32 s19, s17, 1
	s_lshl_b32 s19, s19, 4
	s_add_u32 s16, s16, s19
	v_readlane_b32 s13, v255, 30
	s_nop 3
	s_mul_i32 s13, s13, 0x580000
	s_add_u32 s12, s36, s13
	s_addc_u32 s13, s37, 0
	s_add_u32 s12, s12, 0x226d800
	s_addc_u32 s13, s13, 0
	s_add_u32 s19, s16, s15
	s_mul_i32 s19, s19, 5632
	s_add_u32 s12, s12, s19
	s_addc_u32 s13, s13, 0
	s_lshl_b32 s16, s16, 7
	s_add_u32 s16, s16, 0x10000
	v_lshrrev_b32_e32 v132, 3, v131
	v_and_b32_e32 v133, 7, v131
	v_lshrrev_b32_e32 v134, 4, v131
	v_xor_b32_e32 v133, v133, v134
	v_lshlrev_b32_e32 v133, 4, v133
	v_mul_u32_u24_e32 v134, 5632, v132
	v_or_b32_e32 v226, v134, v133
	v_add_u32_e32 v227, 45056, v226
	v_xor_b32_e32 v227, 64, v227
	v_add_u32_e32 v178, 0x58000, v226
	v_add_u32_e32 v179, 0x58000, v227
	v_mul_u32_u24_e32 v134, 5632, v132
	v_or_b32_e32 v228, v134, v133
	v_add_u32_e32 v214, 45056, v228
	v_xor_b32_e32 v214, 64, v214
	v_add_u32_e32 v203, 0x2c000, v228
	v_add_u32_e32 v204, 0x2c000, v214
	v_and_b32_e32 v132, 31, v131
	v_lshrrev_b32_e32 v133, 5, v131
	v_bfe_u32 v134, v132, 1, 3
	v_and_b32_e32 v135, 1, v134
	v_xor_b32_e32 v133, v133, v135
	v_lshlrev_b32_e32 v133, 4, v133
	v_lshl_add_u32 v133, v132, 7, v133
	v_and_b32_e32 v134, 6, v134
	s_lshr_b32 s19, s17, 2
	s_lshl_b32 s19, s19, 14
	v_xor_b32_e32 v135, 0, v134
	v_lshl_add_u32 v135, v135, 4, v133
	v_add_u32_e32 v246, s19, v135
	v_xor_b32_e32 v135, 2, v134
	v_lshl_add_u32 v135, v135, 4, v133
	v_add_u32_e32 v247, s19, v135
	v_xor_b32_e32 v135, 4, v134
	v_lshl_add_u32 v135, v135, 4, v133
	v_add_u32_e32 v248, s19, v135
	v_xor_b32_e32 v135, 6, v134
	v_lshl_add_u32 v135, v135, 4, v133
	v_add_u32_e32 v249, s19, v135
	s_and_b32 s19, s17, 3
	s_lshl_b32 s19, s19, 13
	s_add_u32 s19, s19, 0x10000
	v_xor_b32_e32 v135, 0, v134
	v_lshl_add_u32 v135, v135, 4, v133
	v_add_u32_e32 v250, s19, v135
	v_xor_b32_e32 v135, 2, v134
	v_lshl_add_u32 v135, v135, 4, v133
	v_add_u32_e32 v251, s19, v135
	v_xor_b32_e32 v135, 4, v134
	v_lshl_add_u32 v135, v135, 4, v133
	v_add_u32_e32 v252, s19, v135
	v_xor_b32_e32 v135, 6, v134
	v_lshl_add_u32 v135, v135, 4, v133
	v_add_u32_e32 v233, s19, v135
	s_add_u32 m0, s16, 0x0
	s_nop 0
	global_load_lds_dwordx4 v228, s[12:13]
	s_add_u32 m0, s16, 0x400
	s_nop 0
	global_load_lds_dwordx4 v214, s[12:13]
	s_add_u32 m0, s4, 0x0
	s_nop 0
	global_load_lds_dwordx4 v226, s[2:3]
	s_add_u32 m0, s4, 0x400
	s_nop 0
	global_load_lds_dwordx4 v227, s[2:3]
	s_add_u32 m0, s16, 0x1000
	s_nop 0
	global_load_lds_dwordx4 v203, s[12:13]
	s_add_u32 m0, s16, 0x1400
	s_nop 0
	global_load_lds_dwordx4 v204, s[12:13]
	s_add_u32 m0, s4, 0x2000
	s_nop 0
	global_load_lds_dwordx4 v178, s[2:3]
	s_add_u32 m0, s4, 0x2400
	s_nop 0
	global_load_lds_dwordx4 v179, s[2:3]
	v_readfirstlane_b32 s19, v200
	s_lshr_b32 s19, s19, 8
	s_cmp_lg_u32 s19, 0
	s_cbranch_scc0 .Lgdn_nolag
	s_barrier

.Lgdn_loop:
	ds_read_b128 v[192:195], v250
	ds_read_b128 v[196:199], v251
	ds_read_b128 v[208:211], v252
	ds_read_b128 v[218:221], v233
	ds_read_b128 v[130:133], v246 offset:0
	ds_read_b128 v[134:137], v247 offset:0
	ds_read_b128 v[138:141], v248 offset:0
	ds_read_b128 v[142:145], v249 offset:0
	ds_read_b128 v[146:149], v246 offset:4096
	ds_read_b128 v[150:153], v247 offset:4096
	ds_read_b128 v[154:157], v248 offset:4096
	ds_read_b128 v[158:161], v249 offset:4096
	s_add_u32 m0, s4, 0xa000
	s_nop 0
	global_load_lds_dwordx4 v178, s[2:3]
	s_add_u32 m0, s4, 0xa400
	s_nop 0
	global_load_lds_dwordx4 v179, s[2:3]
	s_waitcnt lgkmcnt(8)
	s_barrier
	s_waitcnt lgkmcnt(0)
	s_setprio 1
	v_mfma_f32_32x32x16_bf16 v[114:129], v[192:195], v[130:133], v[114:129]
	v_mfma_f32_32x32x16_bf16 v[82:97], v[192:195], v[146:149], v[82:97]
	v_mfma_f32_32x32x16_bf16 v[114:129], v[196:199], v[134:137], v[114:129]
	v_mfma_f32_32x32x16_bf16 v[82:97], v[196:199], v[150:153], v[82:97]
	v_mfma_f32_32x32x16_bf16 v[114:129], v[208:211], v[138:141], v[114:129]
	v_mfma_f32_32x32x16_bf16 v[82:97], v[208:211], v[154:157], v[82:97]
	v_mfma_f32_32x32x16_bf16 v[114:129], v[218:221], v[142:145], v[114:129]
	v_mfma_f32_32x32x16_bf16 v[82:97], v[218:221], v[158:161], v[82:97]
	s_setprio 0
	s_barrier
	ds_read_b128 v[222:225], v250 offset:4096
	ds_read_b128 v[234:237], v251 offset:4096
	ds_read_b128 v[238:241], v252 offset:4096
	ds_read_b128 v[242:245], v233 offset:4096
	s_add_u32 s12, s12, 0x80
	s_addc_u32 s13, s13, 0
	s_add_u32 m0, s16, 0x0
	s_nop 0
	global_load_lds_dwordx4 v228, s[12:13]
	s_add_u32 m0, s16, 0x400
	s_nop 0
	global_load_lds_dwordx4 v214, s[12:13]
	s_barrier
	s_waitcnt lgkmcnt(0)
	s_setprio 1
	v_mfma_f32_32x32x16_bf16 v[98:113], v[222:225], v[130:133], v[98:113]
	v_mfma_f32_32x32x16_bf16 v[66:81], v[222:225], v[146:149], v[66:81]
	v_mfma_f32_32x32x16_bf16 v[98:113], v[234:237], v[134:137], v[98:113]
	v_mfma_f32_32x32x16_bf16 v[66:81], v[234:237], v[150:153], v[66:81]
	v_mfma_f32_32x32x16_bf16 v[98:113], v[238:241], v[138:141], v[98:113]
	v_mfma_f32_32x32x16_bf16 v[66:81], v[238:241], v[154:157], v[66:81]
	v_mfma_f32_32x32x16_bf16 v[98:113], v[242:245], v[142:145], v[98:113]
	v_mfma_f32_32x32x16_bf16 v[66:81], v[242:245], v[158:161], v[66:81]
	s_setprio 0
	s_barrier
	ds_read_b128 v[130:133], v246 offset:8192
	ds_read_b128 v[134:137], v247 offset:8192
	ds_read_b128 v[138:141], v248 offset:8192
	ds_read_b128 v[142:145], v249 offset:8192
	ds_read_b128 v[146:149], v246 offset:12288
	ds_read_b128 v[150:153], v247 offset:12288
	ds_read_b128 v[154:157], v248 offset:12288
	ds_read_b128 v[158:161], v249 offset:12288
	s_add_u32 s2, s2, 0x80
	s_addc_u32 s3, s3, 0
	s_add_u32 m0, s4, 0x0
	s_nop 0
	global_load_lds_dwordx4 v226, s[2:3]
	s_add_u32 m0, s4, 0x400
	s_nop 0
	global_load_lds_dwordx4 v227, s[2:3]
	s_barrier
	s_waitcnt lgkmcnt(0)
	s_setprio 1
	v_mfma_f32_32x32x16_bf16 v[50:65], v[192:195], v[130:133], v[50:65]
	v_mfma_f32_32x32x16_bf16 v[18:33], v[192:195], v[146:149], v[18:33]
	v_mfma_f32_32x32x16_bf16 v[50:65], v[196:199], v[134:137], v[50:65]
	v_mfma_f32_32x32x16_bf16 v[18:33], v[196:199], v[150:153], v[18:33]
	v_mfma_f32_32x32x16_bf16 v[50:65], v[208:211], v[138:141], v[50:65]
	v_mfma_f32_32x32x16_bf16 v[18:33], v[208:211], v[154:157], v[18:33]
	v_mfma_f32_32x32x16_bf16 v[50:65], v[218:221], v[142:145], v[50:65]
	v_mfma_f32_32x32x16_bf16 v[18:33], v[218:221], v[158:161], v[18:33]
	s_setprio 0
	s_barrier
	s_add_u32 m0, s16, 0x1000
	s_nop 0
	global_load_lds_dwordx4 v203, s[12:13]
	s_add_u32 m0, s16, 0x1400
	s_nop 0
	global_load_lds_dwordx4 v204, s[12:13]
	s_waitcnt vmcnt(6)
	s_barrier
	s_setprio 1
	v_mfma_f32_32x32x16_bf16 v[34:49], v[222:225], v[130:133], v[34:49]
	v_mfma_f32_32x32x16_bf16 v[2:17], v[222:225], v[146:149], v[2:17]
	v_mfma_f32_32x32x16_bf16 v[34:49], v[234:237], v[134:137], v[34:49]
	v_mfma_f32_32x32x16_bf16 v[2:17], v[234:237], v[150:153], v[2:17]
	v_mfma_f32_32x32x16_bf16 v[34:49], v[238:241], v[138:141], v[34:49]
	v_mfma_f32_32x32x16_bf16 v[2:17], v[238:241], v[154:157], v[2:17]
	v_mfma_f32_32x32x16_bf16 v[34:49], v[242:245], v[142:145], v[34:49]
	v_mfma_f32_32x32x16_bf16 v[2:17], v[242:245], v[158:161], v[2:17]
	s_setprio 0
	s_barrier
	ds_read_b128 v[192:195], v250 offset:32768
	ds_read_b128 v[196:199], v251 offset:32768
	ds_read_b128 v[208:211], v252 offset:32768
	ds_read_b128 v[218:221], v233 offset:32768
	ds_read_b128 v[130:133], v246 offset:32768
	ds_read_b128 v[134:137], v247 offset:32768
	ds_read_b128 v[138:141], v248 offset:32768
	ds_read_b128 v[142:145], v249 offset:32768
	ds_read_b128 v[146:149], v246 offset:36864
	ds_read_b128 v[150:153], v247 offset:36864
	ds_read_b128 v[154:157], v248 offset:36864
	ds_read_b128 v[158:161], v249 offset:36864
	s_add_u32 m0, s4, 0x2000
	s_nop 0
	global_load_lds_dwordx4 v178, s[2:3]
	s_add_u32 m0, s4, 0x2400
	s_nop 0
	global_load_lds_dwordx4 v179, s[2:3]
	s_waitcnt lgkmcnt(8)
	s_barrier
	s_waitcnt lgkmcnt(0)
	s_setprio 1
	v_mfma_f32_32x32x16_bf16 v[114:129], v[192:195], v[130:133], v[114:129]
	v_mfma_f32_32x32x16_bf16 v[82:97], v[192:195], v[146:149], v[82:97]
	v_mfma_f32_32x32x16_bf16 v[114:129], v[196:199], v[134:137], v[114:129]
	v_mfma_f32_32x32x16_bf16 v[82:97], v[196:199], v[150:153], v[82:97]
	v_mfma_f32_32x32x16_bf16 v[114:129], v[208:211], v[138:141], v[114:129]
	v_mfma_f32_32x32x16_bf16 v[82:97], v[208:211], v[154:157], v[82:97]
	v_mfma_f32_32x32x16_bf16 v[114:129], v[218:221], v[142:145], v[114:129]
	v_mfma_f32_32x32x16_bf16 v[82:97], v[218:221], v[158:161], v[82:97]
	s_setprio 0
	s_barrier
	ds_read_b128 v[222:225], v250 offset:36864
	ds_read_b128 v[234:237], v251 offset:36864
	ds_read_b128 v[238:241], v252 offset:36864
	ds_read_b128 v[242:245], v233 offset:36864
	s_add_u32 s12, s12, 0x80
	s_addc_u32 s13, s13, 0
	s_add_u32 m0, s16, 0x8000
	s_nop 0
	global_load_lds_dwordx4 v228, s[12:13]
	s_add_u32 m0, s16, 0x8400
	s_nop 0
	global_load_lds_dwordx4 v214, s[12:13]
	s_barrier
	s_waitcnt lgkmcnt(0)
	s_setprio 1
	v_mfma_f32_32x32x16_bf16 v[98:113], v[222:225], v[130:133], v[98:113]
	v_mfma_f32_32x32x16_bf16 v[66:81], v[222:225], v[146:149], v[66:81]
	v_mfma_f32_32x32x16_bf16 v[98:113], v[234:237], v[134:137], v[98:113]
	v_mfma_f32_32x32x16_bf16 v[66:81], v[234:237], v[150:153], v[66:81]
	v_mfma_f32_32x32x16_bf16 v[98:113], v[238:241], v[138:141], v[98:113]
	v_mfma_f32_32x32x16_bf16 v[66:81], v[238:241], v[154:157], v[66:81]
	v_mfma_f32_32x32x16_bf16 v[98:113], v[242:245], v[142:145], v[98:113]
	v_mfma_f32_32x32x16_bf16 v[66:81], v[242:245], v[158:161], v[66:81]
	s_setprio 0
	s_barrier
	ds_read_b128 v[130:133], v246 offset:40960
	ds_read_b128 v[134:137], v247 offset:40960
	ds_read_b128 v[138:141], v248 offset:40960
	ds_read_b128 v[142:145], v249 offset:40960
	ds_read_b128 v[146:149], v246 offset:45056
	ds_read_b128 v[150:153], v247 offset:45056
	ds_read_b128 v[154:157], v248 offset:45056
	ds_read_b128 v[158:161], v249 offset:45056
	s_add_u32 s2, s2, 0x80
	s_addc_u32 s3, s3, 0
	s_add_u32 m0, s4, 0x8000
	s_nop 0
	global_load_lds_dwordx4 v226, s[2:3]
	s_add_u32 m0, s4, 0x8400
	s_nop 0
	global_load_lds_dwordx4 v227, s[2:3]
	s_barrier
	s_waitcnt lgkmcnt(0)
	s_setprio 1
	v_mfma_f32_32x32x16_bf16 v[50:65], v[192:195], v[130:133], v[50:65]
	v_mfma_f32_32x32x16_bf16 v[18:33], v[192:195], v[146:149], v[18:33]
	v_mfma_f32_32x32x16_bf16 v[50:65], v[196:199], v[134:137], v[50:65]
	v_mfma_f32_32x32x16_bf16 v[18:33], v[196:199], v[150:153], v[18:33]
	v_mfma_f32_32x32x16_bf16 v[50:65], v[208:211], v[138:141], v[50:65]
	v_mfma_f32_32x32x16_bf16 v[18:33], v[208:211], v[154:157], v[18:33]
	v_mfma_f32_32x32x16_bf16 v[50:65], v[218:221], v[142:145], v[50:65]
	v_mfma_f32_32x32x16_bf16 v[18:33], v[218:221], v[158:161], v[18:33]
	s_setprio 0
	s_barrier
	s_add_u32 m0, s16, 0x9000
	s_nop 0
	global_load_lds_dwordx4 v203, s[12:13]
	s_add_u32 m0, s16, 0x9400
	s_nop 0
	global_load_lds_dwordx4 v204, s[12:13]
	s_waitcnt vmcnt(6)
	s_barrier
	s_setprio 1
	v_mfma_f32_32x32x16_bf16 v[34:49], v[222:225], v[130:133], v[34:49]
	v_mfma_f32_32x32x16_bf16 v[2:17], v[222:225], v[146:149], v[2:17]
	v_mfma_f32_32x32x16_bf16 v[34:49], v[234:237], v[134:137], v[34:49]
	v_mfma_f32_32x32x16_bf16 v[2:17], v[234:237], v[150:153], v[2:17]
	v_mfma_f32_32x32x16_bf16 v[34:49], v[238:241], v[138:141], v[34:49]
	v_mfma_f32_32x32x16_bf16 v[2:17], v[238:241], v[154:157], v[2:17]
	v_mfma_f32_32x32x16_bf16 v[34:49], v[242:245], v[142:145], v[34:49]
	v_mfma_f32_32x32x16_bf16 v[2:17], v[242:245], v[158:161], v[2:17]
	s_setprio 0
	s_barrier
	s_add_i32 s17, s17, 2
	s_cmp_lt_u32 s17, 42
	s_cbranch_scc1 .Lgdn_loop
	ds_read_b128 v[192:195], v250
	ds_read_b128 v[196:199], v251
	ds_read_b128 v[208:211], v252
	ds_read_b128 v[218:221], v233
	ds_read_b128 v[130:133], v246 offset:0
	ds_read_b128 v[134:137], v247 offset:0
	ds_read_b128 v[138:141], v248 offset:0
	ds_read_b128 v[142:145], v249 offset:0
	ds_read_b128 v[146:149], v246 offset:4096
	ds_read_b128 v[150:153], v247 offset:4096
	ds_read_b128 v[154:157], v248 offset:4096
	ds_read_b128 v[158:161], v249 offset:4096
	s_add_u32 m0, s4, 0xa000
	s_nop 0
	global_load_lds_dwordx4 v178, s[2:3]
	s_add_u32 m0, s4, 0xa400
	s_nop 0
	global_load_lds_dwordx4 v179, s[2:3]
	s_barrier
	s_waitcnt lgkmcnt(0)
	s_setprio 1
	v_mfma_f32_32x32x16_bf16 v[114:129], v[192:195], v[130:133], v[114:129]
	v_mfma_f32_32x32x16_bf16 v[82:97], v[192:195], v[146:149], v[82:97]
	v_mfma_f32_32x32x16_bf16 v[114:129], v[196:199], v[134:137], v[114:129]
	v_mfma_f32_32x32x16_bf16 v[82:97], v[196:199], v[150:153], v[82:97]
	v_mfma_f32_32x32x16_bf16 v[114:129], v[208:211], v[138:141], v[114:129]
	v_mfma_f32_32x32x16_bf16 v[82:97], v[208:211], v[154:157], v[82:97]
	v_mfma_f32_32x32x16_bf16 v[114:129], v[218:221], v[142:145], v[114:129]
	v_mfma_f32_32x32x16_bf16 v[82:97], v[218:221], v[158:161], v[82:97]
	s_setprio 0
	s_barrier
	ds_read_b128 v[222:225], v250 offset:4096
	ds_read_b128 v[234:237], v251 offset:4096
	ds_read_b128 v[238:241], v252 offset:4096
	ds_read_b128 v[242:245], v233 offset:4096
	s_barrier
	s_waitcnt lgkmcnt(0)
	s_setprio 1
	v_mfma_f32_32x32x16_bf16 v[98:113], v[222:225], v[130:133], v[98:113]
	v_mfma_f32_32x32x16_bf16 v[66:81], v[222:225], v[146:149], v[66:81]
	v_mfma_f32_32x32x16_bf16 v[98:113], v[234:237], v[134:137], v[98:113]
	v_mfma_f32_32x32x16_bf16 v[66:81], v[234:237], v[150:153], v[66:81]
	v_mfma_f32_32x32x16_bf16 v[98:113], v[238:241], v[138:141], v[98:113]
	v_mfma_f32_32x32x16_bf16 v[66:81], v[238:241], v[154:157], v[66:81]
	v_mfma_f32_32x32x16_bf16 v[98:113], v[242:245], v[142:145], v[98:113]
	v_mfma_f32_32x32x16_bf16 v[66:81], v[242:245], v[158:161], v[66:81]
	s_setprio 0
	s_barrier
	ds_read_b128 v[130:133], v246 offset:8192
	ds_read_b128 v[134:137], v247 offset:8192
	ds_read_b128 v[138:141], v248 offset:8192
	ds_read_b128 v[142:145], v249 offset:8192
	ds_read_b128 v[146:149], v246 offset:12288
	ds_read_b128 v[150:153], v247 offset:12288
	ds_read_b128 v[154:157], v248 offset:12288
	ds_read_b128 v[158:161], v249 offset:12288
	s_waitcnt vmcnt(4)
	s_barrier
	s_waitcnt lgkmcnt(0)
	s_setprio 1
	v_mfma_f32_32x32x16_bf16 v[50:65], v[192:195], v[130:133], v[50:65]
	v_mfma_f32_32x32x16_bf16 v[18:33], v[192:195], v[146:149], v[18:33]
	v_mfma_f32_32x32x16_bf16 v[50:65], v[196:199], v[134:137], v[50:65]
	v_mfma_f32_32x32x16_bf16 v[18:33], v[196:199], v[150:153], v[18:33]
	v_mfma_f32_32x32x16_bf16 v[50:65], v[208:211], v[138:141], v[50:65]
	v_mfma_f32_32x32x16_bf16 v[18:33], v[208:211], v[154:157], v[18:33]
	v_mfma_f32_32x32x16_bf16 v[50:65], v[218:221], v[142:145], v[50:65]
	v_mfma_f32_32x32x16_bf16 v[18:33], v[218:221], v[158:161], v[18:33]
	s_setprio 0
	s_setprio 1
	v_mfma_f32_32x32x16_bf16 v[34:49], v[222:225], v[130:133], v[34:49]
	v_mfma_f32_32x32x16_bf16 v[2:17], v[222:225], v[146:149], v[2:17]
	v_mfma_f32_32x32x16_bf16 v[34:49], v[234:237], v[134:137], v[34:49]
	v_mfma_f32_32x32x16_bf16 v[2:17], v[234:237], v[150:153], v[2:17]
	v_mfma_f32_32x32x16_bf16 v[34:49], v[238:241], v[138:141], v[34:49]
	v_mfma_f32_32x32x16_bf16 v[2:17], v[238:241], v[154:157], v[2:17]
	v_mfma_f32_32x32x16_bf16 v[34:49], v[242:245], v[142:145], v[34:49]
	v_mfma_f32_32x32x16_bf16 v[2:17], v[242:245], v[158:161], v[2:17]
	s_setprio 0
	s_barrier
	ds_read_b128 v[192:195], v250 offset:32768
	ds_read_b128 v[196:199], v251 offset:32768
	ds_read_b128 v[208:211], v252 offset:32768
	ds_read_b128 v[218:221], v233 offset:32768
	ds_read_b128 v[130:133], v246 offset:32768
	ds_read_b128 v[134:137], v247 offset:32768
	ds_read_b128 v[138:141], v248 offset:32768
	ds_read_b128 v[142:145], v249 offset:32768
	ds_read_b128 v[146:149], v246 offset:36864
	ds_read_b128 v[150:153], v247 offset:36864
	ds_read_b128 v[154:157], v248 offset:36864
	ds_read_b128 v[158:161], v249 offset:36864
	s_waitcnt vmcnt(2)
	s_barrier
	s_waitcnt lgkmcnt(0)
	s_setprio 1
	v_mfma_f32_32x32x16_bf16 v[114:129], v[192:195], v[130:133], v[114:129]
	v_mfma_f32_32x32x16_bf16 v[82:97], v[192:195], v[146:149], v[82:97]
	v_mfma_f32_32x32x16_bf16 v[114:129], v[196:199], v[134:137], v[114:129]
	v_mfma_f32_32x32x16_bf16 v[82:97], v[196:199], v[150:153], v[82:97]
	v_mfma_f32_32x32x16_bf16 v[114:129], v[208:211], v[138:141], v[114:129]
	v_mfma_f32_32x32x16_bf16 v[82:97], v[208:211], v[154:157], v[82:97]
	v_mfma_f32_32x32x16_bf16 v[114:129], v[218:221], v[142:145], v[114:129]
	v_mfma_f32_32x32x16_bf16 v[82:97], v[218:221], v[158:161], v[82:97]
	s_setprio 0
	s_barrier
	ds_read_b128 v[222:225], v250 offset:36864
	ds_read_b128 v[234:237], v251 offset:36864
	ds_read_b128 v[238:241], v252 offset:36864
	ds_read_b128 v[242:245], v233 offset:36864
	s_waitcnt vmcnt(0)
	s_barrier
	s_waitcnt lgkmcnt(0)
	s_setprio 1
	v_mfma_f32_32x32x16_bf16 v[98:113], v[222:225], v[130:133], v[98:113]
	v_mfma_f32_32x32x16_bf16 v[66:81], v[222:225], v[146:149], v[66:81]
	v_mfma_f32_32x32x16_bf16 v[98:113], v[234:237], v[134:137], v[98:113]
	v_mfma_f32_32x32x16_bf16 v[66:81], v[234:237], v[150:153], v[66:81]
	v_mfma_f32_32x32x16_bf16 v[98:113], v[238:241], v[138:141], v[98:113]
	v_mfma_f32_32x32x16_bf16 v[66:81], v[238:241], v[154:157], v[66:81]
	v_mfma_f32_32x32x16_bf16 v[98:113], v[242:245], v[142:145], v[98:113]
	v_mfma_f32_32x32x16_bf16 v[66:81], v[242:245], v[158:161], v[66:81]
	s_setprio 0
	s_barrier
	ds_read_b128 v[130:133], v246 offset:40960
	ds_read_b128 v[134:137], v247 offset:40960
	ds_read_b128 v[138:141], v248 offset:40960
	ds_read_b128 v[142:145], v249 offset:40960
	ds_read_b128 v[146:149], v246 offset:45056
	ds_read_b128 v[150:153], v247 offset:45056
	ds_read_b128 v[154:157], v248 offset:45056
	ds_read_b128 v[158:161], v249 offset:45056
	s_barrier
	s_waitcnt lgkmcnt(0)
	s_setprio 1
	v_mfma_f32_32x32x16_bf16 v[50:65], v[192:195], v[130:133], v[50:65]
	v_mfma_f32_32x32x16_bf16 v[18:33], v[192:195], v[146:149], v[18:33]
	v_mfma_f32_32x32x16_bf16 v[50:65], v[196:199], v[134:137], v[50:65]
	v_mfma_f32_32x32x16_bf16 v[18:33], v[196:199], v[150:153], v[18:33]
	v_mfma_f32_32x32x16_bf16 v[50:65], v[208:211], v[138:141], v[50:65]
	v_mfma_f32_32x32x16_bf16 v[18:33], v[208:211], v[154:157], v[18:33]
	v_mfma_f32_32x32x16_bf16 v[50:65], v[218:221], v[142:145], v[50:65]
	v_mfma_f32_32x32x16_bf16 v[18:33], v[218:221], v[158:161], v[18:33]
	s_setprio 0
	s_setprio 1
	v_mfma_f32_32x32x16_bf16 v[34:49], v[222:225], v[130:133], v[34:49]
	v_mfma_f32_32x32x16_bf16 v[2:17], v[222:225], v[146:149], v[2:17]
	v_mfma_f32_32x32x16_bf16 v[34:49], v[234:237], v[134:137], v[34:49]
	v_mfma_f32_32x32x16_bf16 v[2:17], v[234:237], v[150:153], v[2:17]
	v_mfma_f32_32x32x16_bf16 v[34:49], v[238:241], v[138:141], v[34:49]
	v_mfma_f32_32x32x16_bf16 v[2:17], v[238:241], v[154:157], v[2:17]
	v_mfma_f32_32x32x16_bf16 v[34:49], v[242:245], v[142:145], v[34:49]
	v_mfma_f32_32x32x16_bf16 v[2:17], v[242:245], v[158:161], v[2:17]
	s_setprio 0
	s_barrier
	v_readfirstlane_b32 s19, v200
	s_lshr_b32 s19, s19, 8
	s_cmp_lg_u32 s19, 0
	s_cbranch_scc1 .Lgdn_nolag2
	s_barrier

.LBB0_53:
	s_mul_hi_i32 s2, s10, 0x2e8ba2e9
	s_lshr_b32 s3, s2, 31
	s_ashr_i32 s2, s2, 5
	s_add_i32 s17, s2, s3
	s_lshl_b32 s2, s17, 3
	s_sub_i32 s3, s0, s2
	s_min_i32 s3, s3, 8
	s_abs_i32 s14, s3
	v_cvt_f32_u32_e32 v2, s14
	s_sub_i32 s19, 0, s14
	s_mul_i32 s15, s17, 0xffffff50
	s_add_i32 s15, s15, s10
	v_rcp_iflag_f32_e32 v2, v2
	s_abs_i32 s16, s15
	s_xor_b32 s18, s15, s3
	s_ashr_i32 s18, s18, 31
	v_mul_f32_e32 v2, 0x4f7ffffe, v2
	v_cvt_u32_f32_e32 v2, v2
	s_mulk_i32 s17, 0xa8
	s_mov_b32 s4, 0x308d000
	s_mov_b32 s6, 0x30ad000
	v_readfirstlane_b32 s22, v2
	s_mul_i32 s19, s19, s22
	s_mul_hi_u32 s19, s22, s19
	s_add_i32 s22, s22, s19
	s_mul_hi_u32 s19, s16, s22
	s_mul_i32 s22, s19, s14
	s_sub_i32 s16, s16, s22
	s_add_i32 s23, s19, 1
	s_sub_i32 s22, s16, s14
	s_cmp_ge_u32 s16, s14
	s_cselect_b32 s19, s23, s19
	s_cselect_b32 s16, s22, s16
	s_add_i32 s22, s19, 1
	s_cmp_ge_u32 s16, s14
	s_cselect_b32 s14, s22, s19
	s_xor_b32 s14, s14, s18
	s_sub_i32 s16, s14, s18
	s_mul_i32 s18, s16, s3
	s_add_i32 s15, s15, s2
	s_sub_i32 s2, s15, s18
	s_lshl_b32 s14, s2, 8
	v_add_u32_e32 v2, s14, v164
	v_ashrrev_i32_e32 v3, 31, v2
	v_lshlrev_b64 v[2:3], 11, v[2:3]
	s_lshl_b32 s15, s16, 8
	v_lshl_add_u64 v[52:53], v[168:169], 0, v[2:3]
	s_mov_b32 s2, 0x20000
	v_add_u32_e32 v4, s15, v164
	v_add_co_u32_e32 v54, vcc, s2, v52
	v_ashrrev_i32_e32 v5, 31, v4
	s_nop 0
	v_addc_co_u32_e32 v55, vcc, 0, v53, vcc
	s_mov_b32 s3, 0x40000
	v_lshlrev_b64 v[48:49], 11, v[4:5]
	v_add_co_u32_e32 v56, vcc, s3, v52
	v_lshl_add_u64 v[50:51], v[166:167], 0, v[48:49]
	s_nop 0
	v_addc_co_u32_e32 v57, vcc, 0, v53, vcc
	v_add_co_u32_e32 v58, vcc, s2, v50
	s_mov_b32 s2, 0x60000
	s_nop 0
	v_addc_co_u32_e32 v59, vcc, 0, v51, vcc
	v_add_co_u32_e32 v60, vcc, s3, v50
	v_addc_co_u32_e32 v61, vcc, 0, v51, vcc
	v_add_co_u32_e32 v62, vcc, s2, v50
	v_addc_co_u32_e32 v63, vcc, 0, v51, vcc
	v_add_co_u32_e32 v64, vcc, s2, v52
	v_addc_co_u32_e32 v65, vcc, 0, v53, vcc
	s_sub_i32 s18, s10, s18
	s_sub_i32 s17, s18, s17
	s_lshl_b32 s18, s17, 8
	s_ashr_i32 s19, s18, 31
	v_lshl_add_u64 v[178:179], v[174:175], 0, v[48:49]
	v_lshl_add_u64 v[48:49], v[164:165], 0, s[18:19]
	v_mov_b32_e32 v2, 0
	v_lshlrev_b64 v[48:49], 11, v[48:49]
	s_mov_b32 s16, 1
	s_mov_b64 s[2:3], 0
	v_mov_b32_e32 v3, v2
	v_mov_b32_e32 v4, v2
	v_mov_b32_e32 v5, v2
	v_mov_b32_e32 v6, v2
	v_mov_b32_e32 v7, v2
	v_mov_b32_e32 v8, v2
	v_mov_b32_e32 v9, v2
	v_mov_b32_e32 v10, v2
	v_mov_b32_e32 v11, v2
	v_mov_b32_e32 v12, v2
	v_mov_b32_e32 v13, v2
	v_mov_b32_e32 v14, v2
	v_mov_b32_e32 v15, v2
	v_lshl_add_u64 v[180:181], v[176:177], 0, v[48:49]
	v_mov_b32_e32 v48, v2
	v_mov_b32_e32 v49, v2
	v_mov_b32_e32 v50, v2
	v_mov_b32_e32 v51, v2
	v_mov_b32_e32 v52, v2
	v_mov_b32_e32 v53, v2
	v_mov_b32_e32 v54, v2
	v_mov_b32_e32 v55, v2
	v_mov_b32_e32 v56, v2
	v_mov_b32_e32 v57, v2
	v_mov_b32_e32 v58, v2
	v_mov_b32_e32 v59, v2
	v_mov_b32_e32 v60, v2
	v_mov_b32_e32 v61, v2
	v_mov_b32_e32 v62, v2
	v_mov_b32_e32 v63, v2
	v_mov_b32_e32 v16, v2
	v_mov_b32_e32 v17, v2
	v_mov_b32_e32 v34, v2
	v_mov_b32_e32 v35, v2
	v_mov_b32_e32 v36, v2
	v_mov_b32_e32 v37, v2
	v_mov_b32_e32 v38, v2
	v_mov_b32_e32 v39, v2
	v_mov_b32_e32 v40, v2
	v_mov_b32_e32 v41, v2
	v_mov_b32_e32 v42, v2
	v_mov_b32_e32 v43, v2
	v_mov_b32_e32 v44, v2
	v_mov_b32_e32 v45, v2
	v_mov_b32_e32 v46, v2
	v_mov_b32_e32 v47, v2
	v_mov_b32_e32 v18, v2
	v_mov_b32_e32 v19, v2
	v_mov_b32_e32 v20, v2
	v_mov_b32_e32 v21, v2
	v_mov_b32_e32 v22, v2
	v_mov_b32_e32 v23, v2
	v_mov_b32_e32 v24, v2
	v_mov_b32_e32 v25, v2
	v_mov_b32_e32 v26, v2
	v_mov_b32_e32 v27, v2
	v_mov_b32_e32 v28, v2
	v_mov_b32_e32 v29, v2
	v_mov_b32_e32 v30, v2
	v_mov_b32_e32 v31, v2
	v_mov_b32_e32 v32, v2
	v_mov_b32_e32 v33, v2
	v_mov_b32_e32 v64, v2
	v_mov_b32_e32 v65, v2
	v_mov_b32_e32 v66, v2
	v_mov_b32_e32 v67, v2
	v_mov_b32_e32 v68, v2
	v_mov_b32_e32 v69, v2
	v_mov_b32_e32 v70, v2
	v_mov_b32_e32 v71, v2
	v_mov_b32_e32 v72, v2
	v_mov_b32_e32 v73, v2
	v_mov_b32_e32 v74, v2
	v_mov_b32_e32 v75, v2
	v_mov_b32_e32 v76, v2
	v_mov_b32_e32 v77, v2
	v_mov_b32_e32 v78, v2
	v_mov_b32_e32 v79, v2
	v_mov_b32_e32 v80, v2
	v_mov_b32_e32 v81, v2
	v_mov_b32_e32 v98, v2
	v_mov_b32_e32 v99, v2
	v_mov_b32_e32 v100, v2
	v_mov_b32_e32 v101, v2
	v_mov_b32_e32 v102, v2
	v_mov_b32_e32 v103, v2
	v_mov_b32_e32 v104, v2
	v_mov_b32_e32 v105, v2
	v_mov_b32_e32 v106, v2
	v_mov_b32_e32 v107, v2
	v_mov_b32_e32 v108, v2
	v_mov_b32_e32 v109, v2
	v_mov_b32_e32 v110, v2
	v_mov_b32_e32 v111, v2
	v_mov_b32_e32 v112, v2
	v_mov_b32_e32 v113, v2
	v_mov_b32_e32 v82, v2
	v_mov_b32_e32 v83, v2
	v_mov_b32_e32 v84, v2
	v_mov_b32_e32 v85, v2
	v_mov_b32_e32 v86, v2
	v_mov_b32_e32 v87, v2
	v_mov_b32_e32 v88, v2
	v_mov_b32_e32 v89, v2
	v_mov_b32_e32 v90, v2
	v_mov_b32_e32 v91, v2
	v_mov_b32_e32 v92, v2
	v_mov_b32_e32 v93, v2
	v_mov_b32_e32 v94, v2
	v_mov_b32_e32 v95, v2
	v_mov_b32_e32 v96, v2
	v_mov_b32_e32 v97, v2
	v_mov_b32_e32 v114, v2
	v_mov_b32_e32 v115, v2
	v_mov_b32_e32 v116, v2
	v_mov_b32_e32 v117, v2
	v_mov_b32_e32 v118, v2
	v_mov_b32_e32 v119, v2
	v_mov_b32_e32 v120, v2
	v_mov_b32_e32 v121, v2
	v_mov_b32_e32 v122, v2
	v_mov_b32_e32 v123, v2
	v_mov_b32_e32 v124, v2
	v_mov_b32_e32 v125, v2
	v_mov_b32_e32 v126, v2
	v_mov_b32_e32 v127, v2
	v_mov_b32_e32 v128, v2
	v_mov_b32_e32 v129, v2
	s_mov_b32 s7, 0x30cd000
	s_waitcnt lgkmcnt(0)
	v_lshrrev_b32_e32 v130, 6, v200
	v_and_b32_e32 v131, 63, v200
	v_readfirstlane_b32 s17, v130
	s_lshr_b32 s4, s17, 2
	s_lshl_b32 s4, s4, 7
	s_and_b32 s19, s17, 3
	s_lshl_b32 s19, s19, 4
	s_add_u32 s4, s4, s19
	s_add_u32 s19, s4, s14
	s_mul_i32 s19, s19, 2048
	s_add_u32 s2, s36, 0x308d800
	s_addc_u32 s3, s37, 0
	s_add_u32 s2, s2, s19
	s_addc_u32 s3, s3, 0
	s_lshl_b32 s4, s4, 7
	s_lshr_b32 s16, s17, 1
	s_lshl_b32 s16, s16, 6
	s_and_b32 s19, s17, 1
	s_lshl_b32 s19, s19, 4
	s_add_u32 s16, s16, s19
	v_readlane_b32 s7, v255, 30
	s_nop 3
	s_mul_i32 s7, s7, 0xb00000
	s_add_u32 s6, s36, s7
	s_addc_u32 s7, s37, 0
	s_add_u32 s6, s6, 0xc6d800
	s_addc_u32 s7, s7, 0
	s_add_u32 s19, s16, s15
	s_mul_i32 s19, s19, 2048
	s_add_u32 s6, s6, s19
	s_addc_u32 s7, s7, 0
	s_lshl_b32 s16, s16, 7
	s_add_u32 s16, s16, 0x10000
	v_lshrrev_b32_e32 v132, 3, v131
	v_and_b32_e32 v133, 7, v131
	v_lshrrev_b32_e32 v134, 4, v131
	v_xor_b32_e32 v133, v133, v134
	v_lshlrev_b32_e32 v133, 4, v133
	v_mul_u32_u24_e32 v134, 2048, v132
	v_or_b32_e32 v226, v134, v133
	v_add_u32_e32 v227, 16384, v226
	v_xor_b32_e32 v227, 64, v227
	v_add_u32_e32 v178, 0x20000, v226
	v_add_u32_e32 v179, 0x20000, v227
	v_mul_u32_u24_e32 v134, 2048, v132
	v_or_b32_e32 v228, v134, v133
	v_add_u32_e32 v214, 16384, v228
	v_xor_b32_e32 v214, 64, v214
	v_add_u32_e32 v203, 0x10000, v228
	v_add_u32_e32 v204, 0x10000, v214
	v_and_b32_e32 v132, 31, v131
	v_lshrrev_b32_e32 v133, 5, v131
	v_bfe_u32 v134, v132, 1, 3
	v_and_b32_e32 v135, 1, v134
	v_xor_b32_e32 v133, v133, v135
	v_lshlrev_b32_e32 v133, 4, v133
	v_lshl_add_u32 v133, v132, 7, v133
	v_and_b32_e32 v134, 6, v134
	s_lshr_b32 s19, s17, 2
	s_lshl_b32 s19, s19, 14
	v_xor_b32_e32 v135, 0, v134
	v_lshl_add_u32 v135, v135, 4, v133
	v_add_u32_e32 v246, s19, v135
	v_xor_b32_e32 v135, 2, v134
	v_lshl_add_u32 v135, v135, 4, v133
	v_add_u32_e32 v247, s19, v135
	v_xor_b32_e32 v135, 4, v134
	v_lshl_add_u32 v135, v135, 4, v133
	v_add_u32_e32 v248, s19, v135
	v_xor_b32_e32 v135, 6, v134
	v_lshl_add_u32 v135, v135, 4, v133
	v_add_u32_e32 v249, s19, v135
	s_and_b32 s19, s17, 3
	s_lshl_b32 s19, s19, 13
	s_add_u32 s19, s19, 0x10000
	v_xor_b32_e32 v135, 0, v134
	v_lshl_add_u32 v135, v135, 4, v133
	v_add_u32_e32 v250, s19, v135
	v_xor_b32_e32 v135, 2, v134
	v_lshl_add_u32 v135, v135, 4, v133
	v_add_u32_e32 v251, s19, v135
	v_xor_b32_e32 v135, 4, v134
	v_lshl_add_u32 v135, v135, 4, v133
	v_add_u32_e32 v252, s19, v135
	v_xor_b32_e32 v135, 6, v134
	v_lshl_add_u32 v135, v135, 4, v133
	v_add_u32_e32 v233, s19, v135
	s_add_u32 m0, s16, 0x0
	s_nop 0
	global_load_lds_dwordx4 v228, s[6:7]
	s_add_u32 m0, s16, 0x400
	s_nop 0
	global_load_lds_dwordx4 v214, s[6:7]
	s_add_u32 m0, s4, 0x0
	s_nop 0
	global_load_lds_dwordx4 v226, s[2:3]
	s_add_u32 m0, s4, 0x400
	s_nop 0
	global_load_lds_dwordx4 v227, s[2:3]
	s_add_u32 m0, s16, 0x1000
	s_nop 0
	global_load_lds_dwordx4 v203, s[6:7]
	s_add_u32 m0, s16, 0x1400
	s_nop 0
	global_load_lds_dwordx4 v204, s[6:7]
	s_add_u32 m0, s4, 0x2000
	s_nop 0
	global_load_lds_dwordx4 v178, s[2:3]
	s_add_u32 m0, s4, 0x2400
	s_nop 0
	global_load_lds_dwordx4 v179, s[2:3]
	v_readfirstlane_b32 s19, v200
	s_lshr_b32 s19, s19, 8
	s_cmp_lg_u32 s19, 0
	s_cbranch_scc0 .Lggu_nolag
	s_barrier

.Lggu_loop:
	ds_read_b128 v[192:195], v250
	ds_read_b128 v[196:199], v251
	ds_read_b128 v[208:211], v252
	ds_read_b128 v[218:221], v233
	ds_read_b128 v[130:133], v246 offset:0
	ds_read_b128 v[134:137], v247 offset:0
	ds_read_b128 v[138:141], v248 offset:0
	ds_read_b128 v[142:145], v249 offset:0
	ds_read_b128 v[146:149], v246 offset:4096
	ds_read_b128 v[150:153], v247 offset:4096
	ds_read_b128 v[154:157], v248 offset:4096
	ds_read_b128 v[158:161], v249 offset:4096
	s_add_u32 m0, s4, 0xa000
	s_nop 0
	global_load_lds_dwordx4 v178, s[2:3]
	s_add_u32 m0, s4, 0xa400
	s_nop 0
	global_load_lds_dwordx4 v179, s[2:3]
	s_waitcnt lgkmcnt(8)
	s_barrier
	s_waitcnt lgkmcnt(0)
	s_setprio 1
	v_mfma_f32_32x32x16_bf16 v[114:129], v[192:195], v[130:133], v[114:129]
	v_mfma_f32_32x32x16_bf16 v[82:97], v[192:195], v[146:149], v[82:97]
	v_mfma_f32_32x32x16_bf16 v[114:129], v[196:199], v[134:137], v[114:129]
	v_mfma_f32_32x32x16_bf16 v[82:97], v[196:199], v[150:153], v[82:97]
	v_mfma_f32_32x32x16_bf16 v[114:129], v[208:211], v[138:141], v[114:129]
	v_mfma_f32_32x32x16_bf16 v[82:97], v[208:211], v[154:157], v[82:97]
	v_mfma_f32_32x32x16_bf16 v[114:129], v[218:221], v[142:145], v[114:129]
	v_mfma_f32_32x32x16_bf16 v[82:97], v[218:221], v[158:161], v[82:97]
	s_setprio 0
	s_barrier
	ds_read_b128 v[222:225], v250 offset:4096
	ds_read_b128 v[234:237], v251 offset:4096
	ds_read_b128 v[238:241], v252 offset:4096
	ds_read_b128 v[242:245], v233 offset:4096
	s_add_u32 s6, s6, 0x80
	s_addc_u32 s7, s7, 0
	s_add_u32 m0, s16, 0x0
	s_nop 0
	global_load_lds_dwordx4 v228, s[6:7]
	s_add_u32 m0, s16, 0x400
	s_nop 0
	global_load_lds_dwordx4 v214, s[6:7]
	s_barrier
	s_waitcnt lgkmcnt(0)
	s_setprio 1
	v_mfma_f32_32x32x16_bf16 v[98:113], v[222:225], v[130:133], v[98:113]
	v_mfma_f32_32x32x16_bf16 v[66:81], v[222:225], v[146:149], v[66:81]
	v_mfma_f32_32x32x16_bf16 v[98:113], v[234:237], v[134:137], v[98:113]
	v_mfma_f32_32x32x16_bf16 v[66:81], v[234:237], v[150:153], v[66:81]
	v_mfma_f32_32x32x16_bf16 v[98:113], v[238:241], v[138:141], v[98:113]
	v_mfma_f32_32x32x16_bf16 v[66:81], v[238:241], v[154:157], v[66:81]
	v_mfma_f32_32x32x16_bf16 v[98:113], v[242:245], v[142:145], v[98:113]
	v_mfma_f32_32x32x16_bf16 v[66:81], v[242:245], v[158:161], v[66:81]
	s_setprio 0
	s_barrier
	ds_read_b128 v[130:133], v246 offset:8192
	ds_read_b128 v[134:137], v247 offset:8192
	ds_read_b128 v[138:141], v248 offset:8192
	ds_read_b128 v[142:145], v249 offset:8192
	ds_read_b128 v[146:149], v246 offset:12288
	ds_read_b128 v[150:153], v247 offset:12288
	ds_read_b128 v[154:157], v248 offset:12288
	ds_read_b128 v[158:161], v249 offset:12288
	s_add_u32 s2, s2, 0x80
	s_addc_u32 s3, s3, 0
	s_add_u32 m0, s4, 0x0
	s_nop 0
	global_load_lds_dwordx4 v226, s[2:3]
	s_add_u32 m0, s4, 0x400
	s_nop 0
	global_load_lds_dwordx4 v227, s[2:3]
	s_barrier
	s_waitcnt lgkmcnt(0)
	s_setprio 1
	v_mfma_f32_32x32x16_bf16 v[50:65], v[192:195], v[130:133], v[50:65]
	v_mfma_f32_32x32x16_bf16 v[18:33], v[192:195], v[146:149], v[18:33]
	v_mfma_f32_32x32x16_bf16 v[50:65], v[196:199], v[134:137], v[50:65]
	v_mfma_f32_32x32x16_bf16 v[18:33], v[196:199], v[150:153], v[18:33]
	v_mfma_f32_32x32x16_bf16 v[50:65], v[208:211], v[138:141], v[50:65]
	v_mfma_f32_32x32x16_bf16 v[18:33], v[208:211], v[154:157], v[18:33]
	v_mfma_f32_32x32x16_bf16 v[50:65], v[218:221], v[142:145], v[50:65]
	v_mfma_f32_32x32x16_bf16 v[18:33], v[218:221], v[158:161], v[18:33]
	s_setprio 0
	s_barrier
	s_add_u32 m0, s16, 0x1000
	s_nop 0
	global_load_lds_dwordx4 v203, s[6:7]
	s_add_u32 m0, s16, 0x1400
	s_nop 0
	global_load_lds_dwordx4 v204, s[6:7]
	s_waitcnt vmcnt(6)
	s_barrier
	s_setprio 1
	v_mfma_f32_32x32x16_bf16 v[34:49], v[222:225], v[130:133], v[34:49]
	v_mfma_f32_32x32x16_bf16 v[2:17], v[222:225], v[146:149], v[2:17]
	v_mfma_f32_32x32x16_bf16 v[34:49], v[234:237], v[134:137], v[34:49]
	v_mfma_f32_32x32x16_bf16 v[2:17], v[234:237], v[150:153], v[2:17]
	v_mfma_f32_32x32x16_bf16 v[34:49], v[238:241], v[138:141], v[34:49]
	v_mfma_f32_32x32x16_bf16 v[2:17], v[238:241], v[154:157], v[2:17]
	v_mfma_f32_32x32x16_bf16 v[34:49], v[242:245], v[142:145], v[34:49]
	v_mfma_f32_32x32x16_bf16 v[2:17], v[242:245], v[158:161], v[2:17]
	s_setprio 0
	s_barrier
	ds_read_b128 v[192:195], v250 offset:32768
	ds_read_b128 v[196:199], v251 offset:32768
	ds_read_b128 v[208:211], v252 offset:32768
	ds_read_b128 v[218:221], v233 offset:32768
	ds_read_b128 v[130:133], v246 offset:32768
	ds_read_b128 v[134:137], v247 offset:32768
	ds_read_b128 v[138:141], v248 offset:32768
	ds_read_b128 v[142:145], v249 offset:32768
	ds_read_b128 v[146:149], v246 offset:36864
	ds_read_b128 v[150:153], v247 offset:36864
	ds_read_b128 v[154:157], v248 offset:36864
	ds_read_b128 v[158:161], v249 offset:36864
	s_add_u32 m0, s4, 0x2000
	s_nop 0
	global_load_lds_dwordx4 v178, s[2:3]
	s_add_u32 m0, s4, 0x2400
	s_nop 0
	global_load_lds_dwordx4 v179, s[2:3]
	s_waitcnt lgkmcnt(8)
	s_barrier
	s_waitcnt lgkmcnt(0)
	s_setprio 1
	v_mfma_f32_32x32x16_bf16 v[114:129], v[192:195], v[130:133], v[114:129]
	v_mfma_f32_32x32x16_bf16 v[82:97], v[192:195], v[146:149], v[82:97]
	v_mfma_f32_32x32x16_bf16 v[114:129], v[196:199], v[134:137], v[114:129]
	v_mfma_f32_32x32x16_bf16 v[82:97], v[196:199], v[150:153], v[82:97]
	v_mfma_f32_32x32x16_bf16 v[114:129], v[208:211], v[138:141], v[114:129]
	v_mfma_f32_32x32x16_bf16 v[82:97], v[208:211], v[154:157], v[82:97]
	v_mfma_f32_32x32x16_bf16 v[114:129], v[218:221], v[142:145], v[114:129]
	v_mfma_f32_32x32x16_bf16 v[82:97], v[218:221], v[158:161], v[82:97]
	s_setprio 0
	s_barrier
	ds_read_b128 v[222:225], v250 offset:36864
	ds_read_b128 v[234:237], v251 offset:36864
	ds_read_b128 v[238:241], v252 offset:36864
	ds_read_b128 v[242:245], v233 offset:36864
	s_add_u32 s6, s6, 0x80
	s_addc_u32 s7, s7, 0
	s_add_u32 m0, s16, 0x8000
	s_nop 0
	global_load_lds_dwordx4 v228, s[6:7]
	s_add_u32 m0, s16, 0x8400
	s_nop 0
	global_load_lds_dwordx4 v214, s[6:7]
	s_barrier
	s_waitcnt lgkmcnt(0)
	s_setprio 1
	v_mfma_f32_32x32x16_bf16 v[98:113], v[222:225], v[130:133], v[98:113]
	v_mfma_f32_32x32x16_bf16 v[66:81], v[222:225], v[146:149], v[66:81]
	v_mfma_f32_32x32x16_bf16 v[98:113], v[234:237], v[134:137], v[98:113]
	v_mfma_f32_32x32x16_bf16 v[66:81], v[234:237], v[150:153], v[66:81]
	v_mfma_f32_32x32x16_bf16 v[98:113], v[238:241], v[138:141], v[98:113]
	v_mfma_f32_32x32x16_bf16 v[66:81], v[238:241], v[154:157], v[66:81]
	v_mfma_f32_32x32x16_bf16 v[98:113], v[242:245], v[142:145], v[98:113]
	v_mfma_f32_32x32x16_bf16 v[66:81], v[242:245], v[158:161], v[66:81]
	s_setprio 0
	s_barrier
	ds_read_b128 v[130:133], v246 offset:40960
	ds_read_b128 v[134:137], v247 offset:40960
	ds_read_b128 v[138:141], v248 offset:40960
	ds_read_b128 v[142:145], v249 offset:40960
	ds_read_b128 v[146:149], v246 offset:45056
	ds_read_b128 v[150:153], v247 offset:45056
	ds_read_b128 v[154:157], v248 offset:45056
	ds_read_b128 v[158:161], v249 offset:45056
	s_add_u32 s2, s2, 0x80
	s_addc_u32 s3, s3, 0
	s_add_u32 m0, s4, 0x8000
	s_nop 0
	global_load_lds_dwordx4 v226, s[2:3]
	s_add_u32 m0, s4, 0x8400
	s_nop 0
	global_load_lds_dwordx4 v227, s[2:3]
	s_barrier
	s_waitcnt lgkmcnt(0)
	s_setprio 1
	v_mfma_f32_32x32x16_bf16 v[50:65], v[192:195], v[130:133], v[50:65]
	v_mfma_f32_32x32x16_bf16 v[18:33], v[192:195], v[146:149], v[18:33]
	v_mfma_f32_32x32x16_bf16 v[50:65], v[196:199], v[134:137], v[50:65]
	v_mfma_f32_32x32x16_bf16 v[18:33], v[196:199], v[150:153], v[18:33]
	v_mfma_f32_32x32x16_bf16 v[50:65], v[208:211], v[138:141], v[50:65]
	v_mfma_f32_32x32x16_bf16 v[18:33], v[208:211], v[154:157], v[18:33]
	v_mfma_f32_32x32x16_bf16 v[50:65], v[218:221], v[142:145], v[50:65]
	v_mfma_f32_32x32x16_bf16 v[18:33], v[218:221], v[158:161], v[18:33]
	s_setprio 0
	s_barrier
	s_add_u32 m0, s16, 0x9000
	s_nop 0
	global_load_lds_dwordx4 v203, s[6:7]
	s_add_u32 m0, s16, 0x9400
	s_nop 0
	global_load_lds_dwordx4 v204, s[6:7]
	s_waitcnt vmcnt(6)
	s_barrier
	s_setprio 1
	v_mfma_f32_32x32x16_bf16 v[34:49], v[222:225], v[130:133], v[34:49]
	v_mfma_f32_32x32x16_bf16 v[2:17], v[222:225], v[146:149], v[2:17]
	v_mfma_f32_32x32x16_bf16 v[34:49], v[234:237], v[134:137], v[34:49]
	v_mfma_f32_32x32x16_bf16 v[2:17], v[234:237], v[150:153], v[2:17]
	v_mfma_f32_32x32x16_bf16 v[34:49], v[238:241], v[138:141], v[34:49]
	v_mfma_f32_32x32x16_bf16 v[2:17], v[238:241], v[154:157], v[2:17]
	v_mfma_f32_32x32x16_bf16 v[34:49], v[242:245], v[142:145], v[34:49]
	v_mfma_f32_32x32x16_bf16 v[2:17], v[242:245], v[158:161], v[2:17]
	s_setprio 0
	s_barrier
	s_add_i32 s17, s17, 2
	s_cmp_lt_u32 s17, 14
	s_cbranch_scc1 .Lggu_loop
	ds_read_b128 v[192:195], v250
	ds_read_b128 v[196:199], v251
	ds_read_b128 v[208:211], v252
	ds_read_b128 v[218:221], v233
	ds_read_b128 v[130:133], v246 offset:0
	ds_read_b128 v[134:137], v247 offset:0
	ds_read_b128 v[138:141], v248 offset:0
	ds_read_b128 v[142:145], v249 offset:0
	ds_read_b128 v[146:149], v246 offset:4096
	ds_read_b128 v[150:153], v247 offset:4096
	ds_read_b128 v[154:157], v248 offset:4096
	ds_read_b128 v[158:161], v249 offset:4096
	s_add_u32 m0, s4, 0xa000
	s_nop 0
	global_load_lds_dwordx4 v178, s[2:3]
	s_add_u32 m0, s4, 0xa400
	s_nop 0
	global_load_lds_dwordx4 v179, s[2:3]
	s_barrier
	s_waitcnt lgkmcnt(0)
	s_setprio 1
	v_mfma_f32_32x32x16_bf16 v[114:129], v[192:195], v[130:133], v[114:129]
	v_mfma_f32_32x32x16_bf16 v[82:97], v[192:195], v[146:149], v[82:97]
	v_mfma_f32_32x32x16_bf16 v[114:129], v[196:199], v[134:137], v[114:129]
	v_mfma_f32_32x32x16_bf16 v[82:97], v[196:199], v[150:153], v[82:97]
	v_mfma_f32_32x32x16_bf16 v[114:129], v[208:211], v[138:141], v[114:129]
	v_mfma_f32_32x32x16_bf16 v[82:97], v[208:211], v[154:157], v[82:97]
	v_mfma_f32_32x32x16_bf16 v[114:129], v[218:221], v[142:145], v[114:129]
	v_mfma_f32_32x32x16_bf16 v[82:97], v[218:221], v[158:161], v[82:97]
	s_setprio 0
	s_barrier
	ds_read_b128 v[222:225], v250 offset:4096
	ds_read_b128 v[234:237], v251 offset:4096
	ds_read_b128 v[238:241], v252 offset:4096
	ds_read_b128 v[242:245], v233 offset:4096
	s_barrier
	s_waitcnt lgkmcnt(0)
	s_setprio 1
	v_mfma_f32_32x32x16_bf16 v[98:113], v[222:225], v[130:133], v[98:113]
	v_mfma_f32_32x32x16_bf16 v[66:81], v[222:225], v[146:149], v[66:81]
	v_mfma_f32_32x32x16_bf16 v[98:113], v[234:237], v[134:137], v[98:113]
	v_mfma_f32_32x32x16_bf16 v[66:81], v[234:237], v[150:153], v[66:81]
	v_mfma_f32_32x32x16_bf16 v[98:113], v[238:241], v[138:141], v[98:113]
	v_mfma_f32_32x32x16_bf16 v[66:81], v[238:241], v[154:157], v[66:81]
	v_mfma_f32_32x32x16_bf16 v[98:113], v[242:245], v[142:145], v[98:113]
	v_mfma_f32_32x32x16_bf16 v[66:81], v[242:245], v[158:161], v[66:81]
	s_setprio 0
	s_barrier
	ds_read_b128 v[130:133], v246 offset:8192
	ds_read_b128 v[134:137], v247 offset:8192
	ds_read_b128 v[138:141], v248 offset:8192
	ds_read_b128 v[142:145], v249 offset:8192
	ds_read_b128 v[146:149], v246 offset:12288
	ds_read_b128 v[150:153], v247 offset:12288
	ds_read_b128 v[154:157], v248 offset:12288
	ds_read_b128 v[158:161], v249 offset:12288
	s_waitcnt vmcnt(4)
	s_barrier
	s_waitcnt lgkmcnt(0)
	s_setprio 1
	v_mfma_f32_32x32x16_bf16 v[50:65], v[192:195], v[130:133], v[50:65]
	v_mfma_f32_32x32x16_bf16 v[18:33], v[192:195], v[146:149], v[18:33]
	v_mfma_f32_32x32x16_bf16 v[50:65], v[196:199], v[134:137], v[50:65]
	v_mfma_f32_32x32x16_bf16 v[18:33], v[196:199], v[150:153], v[18:33]
	v_mfma_f32_32x32x16_bf16 v[50:65], v[208:211], v[138:141], v[50:65]
	v_mfma_f32_32x32x16_bf16 v[18:33], v[208:211], v[154:157], v[18:33]
	v_mfma_f32_32x32x16_bf16 v[50:65], v[218:221], v[142:145], v[50:65]
	v_mfma_f32_32x32x16_bf16 v[18:33], v[218:221], v[158:161], v[18:33]
	s_setprio 0
	s_setprio 1
	v_mfma_f32_32x32x16_bf16 v[34:49], v[222:225], v[130:133], v[34:49]
	v_mfma_f32_32x32x16_bf16 v[2:17], v[222:225], v[146:149], v[2:17]
	v_mfma_f32_32x32x16_bf16 v[34:49], v[234:237], v[134:137], v[34:49]
	v_mfma_f32_32x32x16_bf16 v[2:17], v[234:237], v[150:153], v[2:17]
	v_mfma_f32_32x32x16_bf16 v[34:49], v[238:241], v[138:141], v[34:49]
	v_mfma_f32_32x32x16_bf16 v[2:17], v[238:241], v[154:157], v[2:17]
	v_mfma_f32_32x32x16_bf16 v[34:49], v[242:245], v[142:145], v[34:49]
	v_mfma_f32_32x32x16_bf16 v[2:17], v[242:245], v[158:161], v[2:17]
	s_setprio 0
	s_barrier
	ds_read_b128 v[192:195], v250 offset:32768
	ds_read_b128 v[196:199], v251 offset:32768
	ds_read_b128 v[208:211], v252 offset:32768
	ds_read_b128 v[218:221], v233 offset:32768
	ds_read_b128 v[130:133], v246 offset:32768
	ds_read_b128 v[134:137], v247 offset:32768
	ds_read_b128 v[138:141], v248 offset:32768
	ds_read_b128 v[142:145], v249 offset:32768
	ds_read_b128 v[146:149], v246 offset:36864
	ds_read_b128 v[150:153], v247 offset:36864
	ds_read_b128 v[154:157], v248 offset:36864
	ds_read_b128 v[158:161], v249 offset:36864
	s_waitcnt vmcnt(2)
	s_barrier
	s_waitcnt lgkmcnt(0)
	s_setprio 1
	v_mfma_f32_32x32x16_bf16 v[114:129], v[192:195], v[130:133], v[114:129]
	v_mfma_f32_32x32x16_bf16 v[82:97], v[192:195], v[146:149], v[82:97]
	v_mfma_f32_32x32x16_bf16 v[114:129], v[196:199], v[134:137], v[114:129]
	v_mfma_f32_32x32x16_bf16 v[82:97], v[196:199], v[150:153], v[82:97]
	v_mfma_f32_32x32x16_bf16 v[114:129], v[208:211], v[138:141], v[114:129]
	v_mfma_f32_32x32x16_bf16 v[82:97], v[208:211], v[154:157], v[82:97]
	v_mfma_f32_32x32x16_bf16 v[114:129], v[218:221], v[142:145], v[114:129]
	v_mfma_f32_32x32x16_bf16 v[82:97], v[218:221], v[158:161], v[82:97]
	s_setprio 0
	s_barrier
	ds_read_b128 v[222:225], v250 offset:36864
	ds_read_b128 v[234:237], v251 offset:36864
	ds_read_b128 v[238:241], v252 offset:36864
	ds_read_b128 v[242:245], v233 offset:36864
	s_waitcnt vmcnt(0)
	s_barrier
	s_waitcnt lgkmcnt(0)
	s_setprio 1
	v_mfma_f32_32x32x16_bf16 v[98:113], v[222:225], v[130:133], v[98:113]
	v_mfma_f32_32x32x16_bf16 v[66:81], v[222:225], v[146:149], v[66:81]
	v_mfma_f32_32x32x16_bf16 v[98:113], v[234:237], v[134:137], v[98:113]
	v_mfma_f32_32x32x16_bf16 v[66:81], v[234:237], v[150:153], v[66:81]
	v_mfma_f32_32x32x16_bf16 v[98:113], v[238:241], v[138:141], v[98:113]
	v_mfma_f32_32x32x16_bf16 v[66:81], v[238:241], v[154:157], v[66:81]
	v_mfma_f32_32x32x16_bf16 v[98:113], v[242:245], v[142:145], v[98:113]
	v_mfma_f32_32x32x16_bf16 v[66:81], v[242:245], v[158:161], v[66:81]
	s_setprio 0
	s_barrier
	ds_read_b128 v[130:133], v246 offset:40960
	ds_read_b128 v[134:137], v247 offset:40960
	ds_read_b128 v[138:141], v248 offset:40960
	ds_read_b128 v[142:145], v249 offset:40960
	ds_read_b128 v[146:149], v246 offset:45056
	ds_read_b128 v[150:153], v247 offset:45056
	ds_read_b128 v[154:157], v248 offset:45056
	ds_read_b128 v[158:161], v249 offset:45056
	s_barrier
	s_waitcnt lgkmcnt(0)
	s_setprio 1
	v_mfma_f32_32x32x16_bf16 v[50:65], v[192:195], v[130:133], v[50:65]
	v_mfma_f32_32x32x16_bf16 v[18:33], v[192:195], v[146:149], v[18:33]
	v_mfma_f32_32x32x16_bf16 v[50:65], v[196:199], v[134:137], v[50:65]
	v_mfma_f32_32x32x16_bf16 v[18:33], v[196:199], v[150:153], v[18:33]
	v_mfma_f32_32x32x16_bf16 v[50:65], v[208:211], v[138:141], v[50:65]
	v_mfma_f32_32x32x16_bf16 v[18:33], v[208:211], v[154:157], v[18:33]
	v_mfma_f32_32x32x16_bf16 v[50:65], v[218:221], v[142:145], v[50:65]
	v_mfma_f32_32x32x16_bf16 v[18:33], v[218:221], v[158:161], v[18:33]
	s_setprio 0
	s_setprio 1
	v_mfma_f32_32x32x16_bf16 v[34:49], v[222:225], v[130:133], v[34:49]
	v_mfma_f32_32x32x16_bf16 v[2:17], v[222:225], v[146:149], v[2:17]
	v_mfma_f32_32x32x16_bf16 v[34:49], v[234:237], v[134:137], v[34:49]
	v_mfma_f32_32x32x16_bf16 v[2:17], v[234:237], v[150:153], v[2:17]
	v_mfma_f32_32x32x16_bf16 v[34:49], v[238:241], v[138:141], v[34:49]
	v_mfma_f32_32x32x16_bf16 v[2:17], v[238:241], v[154:157], v[2:17]
	v_mfma_f32_32x32x16_bf16 v[34:49], v[242:245], v[142:145], v[34:49]
	v_mfma_f32_32x32x16_bf16 v[2:17], v[242:245], v[158:161], v[2:17]
	s_setprio 0
	s_barrier
	v_readfirstlane_b32 s19, v200
	s_lshr_b32 s19, s19, 8
	s_cmp_lg_u32 s19, 0
	s_cbranch_scc1 .Lggu_nolag2
	s_barrier

.LBB0_72:
	s_ashr_i32 s1, s0, 31
	s_lshr_b32 s1, s1, 27
	s_add_i32 s1, s0, s1
	s_ashr_i32 s14, s1, 5
	s_andn2_b32 s1, s1, 31
	s_sub_i32 s1, s0, s1
	s_ashr_i32 s2, s1, 31
	s_lshr_b32 s2, s2, 29
	s_add_i32 s2, s1, s2
	s_ashr_i32 s2, s2, 3
	s_lshl_b32 s3, s14, 11
	s_lshl_b32 s1, s1, 8
	s_add_i32 s1, s1, s3
	s_lshl_b32 s15, s2, 11
	s_sub_i32 s1, s1, s15
	v_add_u32_e32 v2, s1, v165
	v_ashrrev_i32_e32 v3, 31, v2
	v_lshlrev_b64 v[2:3], 11, v[2:3]
	s_lshl_b32 s10, s2, 8
	v_lshl_add_u64 v[52:53], v[168:169], 0, v[2:3]
	s_mov_b32 s2, 0x20000
	v_add_u32_e32 v4, s10, v165
	v_add_co_u32_e32 v54, vcc, s2, v52
	v_ashrrev_i32_e32 v5, 31, v4
	s_nop 0
	v_addc_co_u32_e32 v55, vcc, 0, v53, vcc
	s_mov_b32 s3, 0x40000
	v_lshlrev_b64 v[48:49], 11, v[4:5]
	v_add_co_u32_e32 v56, vcc, s3, v52
	v_lshl_add_u64 v[50:51], v[166:167], 0, v[48:49]
	s_nop 0
	v_addc_co_u32_e32 v57, vcc, 0, v53, vcc
	v_add_co_u32_e32 v58, vcc, s2, v50
	s_mov_b32 s2, 0x60000
	s_nop 0
	v_addc_co_u32_e32 v59, vcc, 0, v51, vcc
	v_add_co_u32_e32 v60, vcc, s3, v50
	v_addc_co_u32_e32 v61, vcc, 0, v51, vcc
	v_add_co_u32_e32 v62, vcc, s2, v50
	v_addc_co_u32_e32 v63, vcc, 0, v51, vcc
	v_add_co_u32_e32 v64, vcc, s2, v52
	v_addc_co_u32_e32 v65, vcc, 0, v53, vcc
	s_mulk_i32 s14, 0x1800
	v_subrev_u32_e32 v15, s15, v191
	v_subrev_u32_e32 v66, s14, v15
	v_ashrrev_i32_e32 v67, 31, v66
	v_mov_b32_e32 v2, 0
	v_lshl_add_u64 v[178:179], v[174:175], 0, v[48:49]
	v_lshlrev_b64 v[48:49], 11, v[66:67]
	s_mov_b64 s[2:3], 0
	s_mov_b32 s13, 1
	v_mov_b32_e32 v3, v2
	v_mov_b32_e32 v4, v2
	v_mov_b32_e32 v5, v2
	v_mov_b32_e32 v6, v2
	v_mov_b32_e32 v7, v2
	v_mov_b32_e32 v8, v2
	v_mov_b32_e32 v9, v2
	v_mov_b32_e32 v10, v2
	v_mov_b32_e32 v11, v2
	v_mov_b32_e32 v12, v2
	v_mov_b32_e32 v13, v2
	v_mov_b32_e32 v14, v2
	v_lshl_add_u64 v[180:181], v[176:177], 0, v[48:49]
	v_mov_b32_e32 v15, v2
	v_mov_b32_e32 v48, v2
	v_mov_b32_e32 v49, v2
	v_mov_b32_e32 v50, v2
	v_mov_b32_e32 v51, v2
	v_mov_b32_e32 v52, v2
	v_mov_b32_e32 v53, v2
	v_mov_b32_e32 v54, v2
	v_mov_b32_e32 v55, v2
	v_mov_b32_e32 v56, v2
	v_mov_b32_e32 v57, v2
	v_mov_b32_e32 v58, v2
	v_mov_b32_e32 v59, v2
	v_mov_b32_e32 v60, v2
	v_mov_b32_e32 v61, v2
	v_mov_b32_e32 v62, v2
	v_mov_b32_e32 v63, v2
	v_mov_b32_e32 v64, v2
	v_mov_b32_e32 v65, v2
	v_mov_b32_e32 v16, v2
	v_mov_b32_e32 v17, v2
	v_mov_b32_e32 v34, v2
	v_mov_b32_e32 v35, v2
	v_mov_b32_e32 v36, v2
	v_mov_b32_e32 v37, v2
	v_mov_b32_e32 v38, v2
	v_mov_b32_e32 v39, v2
	v_mov_b32_e32 v40, v2
	v_mov_b32_e32 v41, v2
	v_mov_b32_e32 v42, v2
	v_mov_b32_e32 v43, v2
	v_mov_b32_e32 v44, v2
	v_mov_b32_e32 v45, v2
	v_mov_b32_e32 v46, v2
	v_mov_b32_e32 v47, v2
	v_mov_b32_e32 v18, v2
	v_mov_b32_e32 v19, v2
	v_mov_b32_e32 v20, v2
	v_mov_b32_e32 v21, v2
	v_mov_b32_e32 v22, v2
	v_mov_b32_e32 v23, v2
	v_mov_b32_e32 v24, v2
	v_mov_b32_e32 v25, v2
	v_mov_b32_e32 v26, v2
	v_mov_b32_e32 v27, v2
	v_mov_b32_e32 v28, v2
	v_mov_b32_e32 v29, v2
	v_mov_b32_e32 v30, v2
	v_mov_b32_e32 v31, v2
	v_mov_b32_e32 v32, v2
	v_mov_b32_e32 v33, v2
	v_mov_b32_e32 v66, v2
	v_mov_b32_e32 v67, v2
	v_mov_b32_e32 v68, v2
	v_mov_b32_e32 v69, v2
	v_mov_b32_e32 v70, v2
	v_mov_b32_e32 v71, v2
	v_mov_b32_e32 v72, v2
	v_mov_b32_e32 v73, v2
	v_mov_b32_e32 v74, v2
	v_mov_b32_e32 v75, v2
	v_mov_b32_e32 v76, v2
	v_mov_b32_e32 v77, v2
	v_mov_b32_e32 v78, v2
	v_mov_b32_e32 v79, v2
	v_mov_b32_e32 v80, v2
	v_mov_b32_e32 v81, v2
	v_mov_b32_e32 v98, v2
	v_mov_b32_e32 v99, v2
	v_mov_b32_e32 v100, v2
	v_mov_b32_e32 v101, v2
	v_mov_b32_e32 v102, v2
	v_mov_b32_e32 v103, v2
	v_mov_b32_e32 v104, v2
	v_mov_b32_e32 v105, v2
	v_mov_b32_e32 v106, v2
	v_mov_b32_e32 v107, v2
	v_mov_b32_e32 v108, v2
	v_mov_b32_e32 v109, v2
	v_mov_b32_e32 v110, v2
	v_mov_b32_e32 v111, v2
	v_mov_b32_e32 v112, v2
	v_mov_b32_e32 v113, v2
	v_mov_b32_e32 v82, v2
	v_mov_b32_e32 v83, v2
	v_mov_b32_e32 v84, v2
	v_mov_b32_e32 v85, v2
	v_mov_b32_e32 v86, v2
	v_mov_b32_e32 v87, v2
	v_mov_b32_e32 v88, v2
	v_mov_b32_e32 v89, v2
	v_mov_b32_e32 v90, v2
	v_mov_b32_e32 v91, v2
	v_mov_b32_e32 v92, v2
	v_mov_b32_e32 v93, v2
	v_mov_b32_e32 v94, v2
	v_mov_b32_e32 v95, v2
	v_mov_b32_e32 v96, v2
	v_mov_b32_e32 v97, v2
	v_mov_b32_e32 v114, v2
	v_mov_b32_e32 v115, v2
	v_mov_b32_e32 v116, v2
	v_mov_b32_e32 v117, v2
	v_mov_b32_e32 v118, v2
	v_mov_b32_e32 v119, v2
	v_mov_b32_e32 v120, v2
	v_mov_b32_e32 v121, v2
	v_mov_b32_e32 v122, v2
	v_mov_b32_e32 v123, v2
	v_mov_b32_e32 v124, v2
	v_mov_b32_e32 v125, v2
	v_mov_b32_e32 v126, v2
	v_mov_b32_e32 v127, v2
	v_mov_b32_e32 v128, v2
	v_mov_b32_e32 v129, v2
	s_mov_b32 s4, 0x308d000
	s_mov_b32 s5, 0x30ad000
	s_mov_b32 s6, 0x30cd000
	s_waitcnt lgkmcnt(0)
	v_lshrrev_b32_e32 v130, 6, v200
	v_and_b32_e32 v131, 63, v200
	v_readfirstlane_b32 s14, v130
	s_lshr_b32 s6, s14, 2
	s_lshl_b32 s6, s6, 7
	s_and_b32 s15, s14, 3
	s_lshl_b32 s15, s15, 4
	s_add_u32 s6, s6, s15
	s_add_u32 s15, s6, s1
	s_mul_i32 s15, s15, 2048
	s_add_u32 s2, s36, 0x308d800
	s_addc_u32 s3, s37, 0
	s_add_u32 s2, s2, s15
	s_addc_u32 s3, s3, 0
	s_lshl_b32 s6, s6, 7
	s_lshr_b32 s13, s14, 1
	s_lshl_b32 s13, s13, 6
	s_and_b32 s15, s14, 1
	s_lshl_b32 s15, s15, 4
	s_add_u32 s13, s13, s15
	v_readlane_b32 s5, v255, 30
	s_nop 3
	s_mul_i32 s5, s5, 0x200000
	s_add_u32 s4, s36, s5
	s_addc_u32 s5, s37, 0
	s_add_u32 s4, s4, 0x86d800
	s_addc_u32 s5, s5, 0
	s_add_u32 s15, s13, s10
	s_mul_i32 s15, s15, 2048
	s_add_u32 s4, s4, s15
	s_addc_u32 s5, s5, 0
	s_lshl_b32 s13, s13, 7
	s_add_u32 s13, s13, 0x10000
	v_lshrrev_b32_e32 v132, 3, v131
	v_and_b32_e32 v133, 7, v131
	v_lshrrev_b32_e32 v134, 4, v131
	v_xor_b32_e32 v133, v133, v134
	v_lshlrev_b32_e32 v133, 4, v133
	v_mul_u32_u24_e32 v134, 2048, v132
	v_or_b32_e32 v226, v134, v133
	v_add_u32_e32 v227, 16384, v226
	v_xor_b32_e32 v227, 64, v227
	v_add_u32_e32 v178, 0x20000, v226
	v_add_u32_e32 v179, 0x20000, v227
	v_mul_u32_u24_e32 v134, 2048, v132
	v_or_b32_e32 v228, v134, v133
	v_add_u32_e32 v214, 16384, v228
	v_xor_b32_e32 v214, 64, v214
	v_add_u32_e32 v203, 0x10000, v228
	v_add_u32_e32 v204, 0x10000, v214
	v_and_b32_e32 v132, 31, v131
	v_lshrrev_b32_e32 v133, 5, v131
	v_bfe_u32 v134, v132, 1, 3
	v_and_b32_e32 v135, 1, v134
	v_xor_b32_e32 v133, v133, v135
	v_lshlrev_b32_e32 v133, 4, v133
	v_lshl_add_u32 v133, v132, 7, v133
	v_and_b32_e32 v134, 6, v134
	s_lshr_b32 s15, s14, 2
	s_lshl_b32 s15, s15, 14
	v_xor_b32_e32 v135, 0, v134
	v_lshl_add_u32 v135, v135, 4, v133
	v_add_u32_e32 v246, s15, v135
	v_xor_b32_e32 v135, 2, v134
	v_lshl_add_u32 v135, v135, 4, v133
	v_add_u32_e32 v247, s15, v135
	v_xor_b32_e32 v135, 4, v134
	v_lshl_add_u32 v135, v135, 4, v133
	v_add_u32_e32 v248, s15, v135
	v_xor_b32_e32 v135, 6, v134
	v_lshl_add_u32 v135, v135, 4, v133
	v_add_u32_e32 v249, s15, v135
	s_and_b32 s15, s14, 3
	s_lshl_b32 s15, s15, 13
	s_add_u32 s15, s15, 0x10000
	v_xor_b32_e32 v135, 0, v134
	v_lshl_add_u32 v135, v135, 4, v133
	v_add_u32_e32 v250, s15, v135
	v_xor_b32_e32 v135, 2, v134
	v_lshl_add_u32 v135, v135, 4, v133
	v_add_u32_e32 v251, s15, v135
	v_xor_b32_e32 v135, 4, v134
	v_lshl_add_u32 v135, v135, 4, v133
	v_add_u32_e32 v252, s15, v135
	v_xor_b32_e32 v135, 6, v134
	v_lshl_add_u32 v135, v135, 4, v133
	v_add_u32_e32 v233, s15, v135
	s_add_u32 m0, s13, 0x0
	s_nop 0
	global_load_lds_dwordx4 v228, s[4:5]
	s_add_u32 m0, s13, 0x400
	s_nop 0
	global_load_lds_dwordx4 v214, s[4:5]
	s_add_u32 m0, s6, 0x0
	s_nop 0
	global_load_lds_dwordx4 v226, s[2:3]
	s_add_u32 m0, s6, 0x400
	s_nop 0
	global_load_lds_dwordx4 v227, s[2:3]
	s_add_u32 m0, s13, 0x1000
	s_nop 0
	global_load_lds_dwordx4 v203, s[4:5]
	s_add_u32 m0, s13, 0x1400
	s_nop 0
	global_load_lds_dwordx4 v204, s[4:5]
	s_add_u32 m0, s6, 0x2000
	s_nop 0
	global_load_lds_dwordx4 v178, s[2:3]
	s_add_u32 m0, s6, 0x2400
	s_nop 0
	global_load_lds_dwordx4 v179, s[2:3]
	v_readfirstlane_b32 s15, v200
	s_lshr_b32 s15, s15, 8
	s_cmp_lg_u32 s15, 0
	s_cbranch_scc0 .Lgou_nolag
	s_barrier
.Lgou_nolag:
	s_waitcnt vmcnt(4)
	s_barrier
	s_add_u32 s4, s4, 0x80
	s_addc_u32 s5, s5, 0
	s_add_u32 m0, s13, 0x8000
	s_nop 0
	global_load_lds_dwordx4 v228, s[4:5]
	s_add_u32 m0, s13, 0x8400
	s_nop 0
	global_load_lds_dwordx4 v214, s[4:5]
	s_add_u32 s2, s2, 0x80
	s_addc_u32 s3, s3, 0
	s_add_u32 m0, s6, 0x8000
	s_nop 0
	global_load_lds_dwordx4 v226, s[2:3]
	s_add_u32 m0, s6, 0x8400
	s_nop 0
	global_load_lds_dwordx4 v227, s[2:3]
	s_add_u32 m0, s13, 0x9000
	s_nop 0
	global_load_lds_dwordx4 v203, s[4:5]
	s_add_u32 m0, s13, 0x9400
	s_nop 0
	global_load_lds_dwordx4 v204, s[4:5]
	s_waitcnt vmcnt(6)
	s_barrier
	s_mov_b32 s14, 0
.Lgou_loop:
	ds_read_b128 v[192:195], v250
	ds_read_b128 v[196:199], v251
	ds_read_b128 v[208:211], v252
	ds_read_b128 v[218:221], v233
	ds_read_b128 v[130:133], v246 offset:0
	ds_read_b128 v[134:137], v247 offset:0
	ds_read_b128 v[138:141], v248 offset:0
	ds_read_b128 v[142:145], v249 offset:0
	ds_read_b128 v[146:149], v246 offset:4096
	ds_read_b128 v[150:153], v247 offset:4096
	ds_read_b128 v[154:157], v248 offset:4096
	ds_read_b128 v[158:161], v249 offset:4096
	s_add_u32 m0, s6, 0xa000
	s_nop 0
	global_load_lds_dwordx4 v178, s[2:3]
	s_add_u32 m0, s6, 0xa400
	s_nop 0
	global_load_lds_dwordx4 v179, s[2:3]
	s_waitcnt lgkmcnt(8)
	s_barrier
	s_waitcnt lgkmcnt(0)
	s_setprio 1
	v_mfma_f32_32x32x16_bf16 v[114:129], v[192:195], v[130:133], v[114:129]
	v_mfma_f32_32x32x16_bf16 v[82:97], v[192:195], v[146:149], v[82:97]
	v_mfma_f32_32x32x16_bf16 v[114:129], v[196:199], v[134:137], v[114:129]
	v_mfma_f32_32x32x16_bf16 v[82:97], v[196:199], v[150:153], v[82:97]
	v_mfma_f32_32x32x16_bf16 v[114:129], v[208:211], v[138:141], v[114:129]
	v_mfma_f32_32x32x16_bf16 v[82:97], v[208:211], v[154:157], v[82:97]
	v_mfma_f32_32x32x16_bf16 v[114:129], v[218:221], v[142:145], v[114:129]
	v_mfma_f32_32x32x16_bf16 v[82:97], v[218:221], v[158:161], v[82:97]
	s_setprio 0
	s_barrier
	ds_read_b128 v[222:225], v250 offset:4096
	ds_read_b128 v[234:237], v251 offset:4096
	ds_read_b128 v[238:241], v252 offset:4096
	ds_read_b128 v[242:245], v233 offset:4096
	s_add_u32 s4, s4, 0x80
	s_addc_u32 s5, s5, 0
	s_add_u32 m0, s13, 0x0
	s_nop 0
	global_load_lds_dwordx4 v228, s[4:5]
	s_add_u32 m0, s13, 0x400
	s_nop 0
	global_load_lds_dwordx4 v214, s[4:5]
	s_barrier
	s_waitcnt lgkmcnt(0)
	s_setprio 1
	v_mfma_f32_32x32x16_bf16 v[98:113], v[222:225], v[130:133], v[98:113]
	v_mfma_f32_32x32x16_bf16 v[66:81], v[222:225], v[146:149], v[66:81]
	v_mfma_f32_32x32x16_bf16 v[98:113], v[234:237], v[134:137], v[98:113]
	v_mfma_f32_32x32x16_bf16 v[66:81], v[234:237], v[150:153], v[66:81]
	v_mfma_f32_32x32x16_bf16 v[98:113], v[238:241], v[138:141], v[98:113]
	v_mfma_f32_32x32x16_bf16 v[66:81], v[238:241], v[154:157], v[66:81]
	v_mfma_f32_32x32x16_bf16 v[98:113], v[242:245], v[142:145], v[98:113]
	v_mfma_f32_32x32x16_bf16 v[66:81], v[242:245], v[158:161], v[66:81]
	s_setprio 0
	s_barrier
	ds_read_b128 v[130:133], v246 offset:8192
	ds_read_b128 v[134:137], v247 offset:8192
	ds_read_b128 v[138:141], v248 offset:8192
	ds_read_b128 v[142:145], v249 offset:8192
	ds_read_b128 v[146:149], v246 offset:12288
	ds_read_b128 v[150:153], v247 offset:12288
	ds_read_b128 v[154:157], v248 offset:12288
	ds_read_b128 v[158:161], v249 offset:12288
	s_add_u32 s2, s2, 0x80
	s_addc_u32 s3, s3, 0
	s_add_u32 m0, s6, 0x0
	s_nop 0
	global_load_lds_dwordx4 v226, s[2:3]
	s_add_u32 m0, s6, 0x400
	s_nop 0
	global_load_lds_dwordx4 v227, s[2:3]
	s_barrier
	s_waitcnt lgkmcnt(0)
	s_setprio 1
	v_mfma_f32_32x32x16_bf16 v[50:65], v[192:195], v[130:133], v[50:65]
	v_mfma_f32_32x32x16_bf16 v[18:33], v[192:195], v[146:149], v[18:33]
	v_mfma_f32_32x32x16_bf16 v[50:65], v[196:199], v[134:137], v[50:65]
	v_mfma_f32_32x32x16_bf16 v[18:33], v[196:199], v[150:153], v[18:33]
	v_mfma_f32_32x32x16_bf16 v[50:65], v[208:211], v[138:141], v[50:65]
	v_mfma_f32_32x32x16_bf16 v[18:33], v[208:211], v[154:157], v[18:33]
	v_mfma_f32_32x32x16_bf16 v[50:65], v[218:221], v[142:145], v[50:65]
	v_mfma_f32_32x32x16_bf16 v[18:33], v[218:221], v[158:161], v[18:33]
	s_setprio 0
	s_barrier
	s_add_u32 m0, s13, 0x1000
	s_nop 0
	global_load_lds_dwordx4 v203, s[4:5]
	s_add_u32 m0, s13, 0x1400
	s_nop 0
	global_load_lds_dwordx4 v204, s[4:5]
	s_waitcnt vmcnt(6)
	s_barrier
	s_setprio 1
	v_mfma_f32_32x32x16_bf16 v[34:49], v[222:225], v[130:133], v[34:49]
	v_mfma_f32_32x32x16_bf16 v[2:17], v[222:225], v[146:149], v[2:17]
	v_mfma_f32_32x32x16_bf16 v[34:49], v[234:237], v[134:137], v[34:49]
	v_mfma_f32_32x32x16_bf16 v[2:17], v[234:237], v[150:153], v[2:17]
	v_mfma_f32_32x32x16_bf16 v[34:49], v[238:241], v[138:141], v[34:49]
	v_mfma_f32_32x32x16_bf16 v[2:17], v[238:241], v[154:157], v[2:17]
	v_mfma_f32_32x32x16_bf16 v[34:49], v[242:245], v[142:145], v[34:49]
	v_mfma_f32_32x32x16_bf16 v[2:17], v[242:245], v[158:161], v[2:17]
	s_setprio 0
	s_barrier
	ds_read_b128 v[192:195], v250 offset:32768
	ds_read_b128 v[196:199], v251 offset:32768
	ds_read_b128 v[208:211], v252 offset:32768
	ds_read_b128 v[218:221], v233 offset:32768
	ds_read_b128 v[130:133], v246 offset:32768
	ds_read_b128 v[134:137], v247 offset:32768
	ds_read_b128 v[138:141], v248 offset:32768
	ds_read_b128 v[142:145], v249 offset:32768
	ds_read_b128 v[146:149], v246 offset:36864
	ds_read_b128 v[150:153], v247 offset:36864
	ds_read_b128 v[154:157], v248 offset:36864
	ds_read_b128 v[158:161], v249 offset:36864
	s_add_u32 m0, s6, 0x2000
	s_nop 0
	global_load_lds_dwordx4 v178, s[2:3]
	s_add_u32 m0, s6, 0x2400
	s_nop 0
	global_load_lds_dwordx4 v179, s[2:3]
	s_waitcnt lgkmcnt(8)
	s_barrier
	s_waitcnt lgkmcnt(0)
	s_setprio 1
	v_mfma_f32_32x32x16_bf16 v[114:129], v[192:195], v[130:133], v[114:129]
	v_mfma_f32_32x32x16_bf16 v[82:97], v[192:195], v[146:149], v[82:97]
	v_mfma_f32_32x32x16_bf16 v[114:129], v[196:199], v[134:137], v[114:129]
	v_mfma_f32_32x32x16_bf16 v[82:97], v[196:199], v[150:153], v[82:97]
	v_mfma_f32_32x32x16_bf16 v[114:129], v[208:211], v[138:141], v[114:129]
	v_mfma_f32_32x32x16_bf16 v[82:97], v[208:211], v[154:157], v[82:97]
	v_mfma_f32_32x32x16_bf16 v[114:129], v[218:221], v[142:145], v[114:129]
	v_mfma_f32_32x32x16_bf16 v[82:97], v[218:221], v[158:161], v[82:97]
	s_setprio 0
	s_barrier
	ds_read_b128 v[222:225], v250 offset:36864
	ds_read_b128 v[234:237], v251 offset:36864
	ds_read_b128 v[238:241], v252 offset:36864
	ds_read_b128 v[242:245], v233 offset:36864
	s_add_u32 s4, s4, 0x80
	s_addc_u32 s5, s5, 0
	s_add_u32 m0, s13, 0x8000
	s_nop 0
	global_load_lds_dwordx4 v228, s[4:5]
	s_add_u32 m0, s13, 0x8400
	s_nop 0
	global_load_lds_dwordx4 v214, s[4:5]
	s_barrier
	s_waitcnt lgkmcnt(0)
	s_setprio 1
	v_mfma_f32_32x32x16_bf16 v[98:113], v[222:225], v[130:133], v[98:113]
	v_mfma_f32_32x32x16_bf16 v[66:81], v[222:225], v[146:149], v[66:81]
	v_mfma_f32_32x32x16_bf16 v[98:113], v[234:237], v[134:137], v[98:113]
	v_mfma_f32_32x32x16_bf16 v[66:81], v[234:237], v[150:153], v[66:81]
	v_mfma_f32_32x32x16_bf16 v[98:113], v[238:241], v[138:141], v[98:113]
	v_mfma_f32_32x32x16_bf16 v[66:81], v[238:241], v[154:157], v[66:81]
	v_mfma_f32_32x32x16_bf16 v[98:113], v[242:245], v[142:145], v[98:113]
	v_mfma_f32_32x32x16_bf16 v[66:81], v[242:245], v[158:161], v[66:81]
	s_setprio 0
	s_barrier
	ds_read_b128 v[130:133], v246 offset:40960
	ds_read_b128 v[134:137], v247 offset:40960
	ds_read_b128 v[138:141], v248 offset:40960
	ds_read_b128 v[142:145], v249 offset:40960
	ds_read_b128 v[146:149], v246 offset:45056
	ds_read_b128 v[150:153], v247 offset:45056
	ds_read_b128 v[154:157], v248 offset:45056
	ds_read_b128 v[158:161], v249 offset:45056
	s_add_u32 s2, s2, 0x80
	s_addc_u32 s3, s3, 0
	s_add_u32 m0, s6, 0x8000
	s_nop 0
	global_load_lds_dwordx4 v226, s[2:3]
	s_add_u32 m0, s6, 0x8400
	s_nop 0
	global_load_lds_dwordx4 v227, s[2:3]
	s_barrier
	s_waitcnt lgkmcnt(0)
	s_setprio 1
	v_mfma_f32_32x32x16_bf16 v[50:65], v[192:195], v[130:133], v[50:65]
	v_mfma_f32_32x32x16_bf16 v[18:33], v[192:195], v[146:149], v[18:33]
	v_mfma_f32_32x32x16_bf16 v[50:65], v[196:199], v[134:137], v[50:65]
	v_mfma_f32_32x32x16_bf16 v[18:33], v[196:199], v[150:153], v[18:33]
	v_mfma_f32_32x32x16_bf16 v[50:65], v[208:211], v[138:141], v[50:65]
	v_mfma_f32_32x32x16_bf16 v[18:33], v[208:211], v[154:157], v[18:33]
	v_mfma_f32_32x32x16_bf16 v[50:65], v[218:221], v[142:145], v[50:65]
	v_mfma_f32_32x32x16_bf16 v[18:33], v[218:221], v[158:161], v[18:33]
	s_setprio 0
	s_barrier
	s_add_u32 m0, s13, 0x9000
	s_nop 0
	global_load_lds_dwordx4 v203, s[4:5]
	s_add_u32 m0, s13, 0x9400
	s_nop 0
	global_load_lds_dwordx4 v204, s[4:5]
	s_waitcnt vmcnt(6)
	s_barrier
	s_setprio 1
	v_mfma_f32_32x32x16_bf16 v[34:49], v[222:225], v[130:133], v[34:49]
	v_mfma_f32_32x32x16_bf16 v[2:17], v[222:225], v[146:149], v[2:17]
	v_mfma_f32_32x32x16_bf16 v[34:49], v[234:237], v[134:137], v[34:49]
	v_mfma_f32_32x32x16_bf16 v[2:17], v[234:237], v[150:153], v[2:17]
	v_mfma_f32_32x32x16_bf16 v[34:49], v[238:241], v[138:141], v[34:49]
	v_mfma_f32_32x32x16_bf16 v[2:17], v[238:241], v[154:157], v[2:17]
	v_mfma_f32_32x32x16_bf16 v[34:49], v[242:245], v[142:145], v[34:49]
	v_mfma_f32_32x32x16_bf16 v[2:17], v[242:245], v[158:161], v[2:17]
	s_setprio 0
	s_barrier
	s_add_i32 s14, s14, 2
	s_cmp_lt_u32 s14, 14
	s_cbranch_scc1 .Lgou_loop
	ds_read_b128 v[192:195], v250
	ds_read_b128 v[196:199], v251
	ds_read_b128 v[208:211], v252
	ds_read_b128 v[218:221], v233
	ds_read_b128 v[130:133], v246 offset:0
	ds_read_b128 v[134:137], v247 offset:0
	ds_read_b128 v[138:141], v248 offset:0
	ds_read_b128 v[142:145], v249 offset:0
	ds_read_b128 v[146:149], v246 offset:4096
	ds_read_b128 v[150:153], v247 offset:4096
	ds_read_b128 v[154:157], v248 offset:4096
	ds_read_b128 v[158:161], v249 offset:4096
	s_add_u32 m0, s6, 0xa000
	s_nop 0
	global_load_lds_dwordx4 v178, s[2:3]
	s_add_u32 m0, s6, 0xa400
	s_nop 0
	global_load_lds_dwordx4 v179, s[2:3]
	s_barrier
	s_waitcnt lgkmcnt(0)
	s_setprio 1
	v_mfma_f32_32x32x16_bf16 v[114:129], v[192:195], v[130:133], v[114:129]
	v_mfma_f32_32x32x16_bf16 v[82:97], v[192:195], v[146:149], v[82:97]
	v_mfma_f32_32x32x16_bf16 v[114:129], v[196:199], v[134:137], v[114:129]
	v_mfma_f32_32x32x16_bf16 v[82:97], v[196:199], v[150:153], v[82:97]
	v_mfma_f32_32x32x16_bf16 v[114:129], v[208:211], v[138:141], v[114:129]
	v_mfma_f32_32x32x16_bf16 v[82:97], v[208:211], v[154:157], v[82:97]
	v_mfma_f32_32x32x16_bf16 v[114:129], v[218:221], v[142:145], v[114:129]
	v_mfma_f32_32x32x16_bf16 v[82:97], v[218:221], v[158:161], v[82:97]
	s_setprio 0
	s_barrier
	ds_read_b128 v[222:225], v250 offset:4096
	ds_read_b128 v[234:237], v251 offset:4096
	ds_read_b128 v[238:241], v252 offset:4096
	ds_read_b128 v[242:245], v233 offset:4096
	s_barrier
	s_waitcnt lgkmcnt(0)
	s_setprio 1
	v_mfma_f32_32x32x16_bf16 v[98:113], v[222:225], v[130:133], v[98:113]
	v_mfma_f32_32x32x16_bf16 v[66:81], v[222:225], v[146:149], v[66:81]
	v_mfma_f32_32x32x16_bf16 v[98:113], v[234:237], v[134:137], v[98:113]
	v_mfma_f32_32x32x16_bf16 v[66:81], v[234:237], v[150:153], v[66:81]
	v_mfma_f32_32x32x16_bf16 v[98:113], v[238:241], v[138:141], v[98:113]
	v_mfma_f32_32x32x16_bf16 v[66:81], v[238:241], v[154:157], v[66:81]
	v_mfma_f32_32x32x16_bf16 v[98:113], v[242:245], v[142:145], v[98:113]
	v_mfma_f32_32x32x16_bf16 v[66:81], v[242:245], v[158:161], v[66:81]
	s_setprio 0
	s_barrier
	ds_read_b128 v[130:133], v246 offset:8192
	ds_read_b128 v[134:137], v247 offset:8192
	ds_read_b128 v[138:141], v248 offset:8192
	ds_read_b128 v[142:145], v249 offset:8192
	ds_read_b128 v[146:149], v246 offset:12288
	ds_read_b128 v[150:153], v247 offset:12288
	ds_read_b128 v[154:157], v248 offset:12288
	ds_read_b128 v[158:161], v249 offset:12288
	s_waitcnt vmcnt(4)
	s_barrier
	s_waitcnt lgkmcnt(0)
	s_setprio 1
	v_mfma_f32_32x32x16_bf16 v[50:65], v[192:195], v[130:133], v[50:65]
	v_mfma_f32_32x32x16_bf16 v[18:33], v[192:195], v[146:149], v[18:33]
	v_mfma_f32_32x32x16_bf16 v[50:65], v[196:199], v[134:137], v[50:65]
	v_mfma_f32_32x32x16_bf16 v[18:33], v[196:199], v[150:153], v[18:33]
	v_mfma_f32_32x32x16_bf16 v[50:65], v[208:211], v[138:141], v[50:65]
	v_mfma_f32_32x32x16_bf16 v[18:33], v[208:211], v[154:157], v[18:33]
	v_mfma_f32_32x32x16_bf16 v[50:65], v[218:221], v[142:145], v[50:65]
	v_mfma_f32_32x32x16_bf16 v[18:33], v[218:221], v[158:161], v[18:33]
	s_setprio 0
	s_setprio 1
	v_mfma_f32_32x32x16_bf16 v[34:49], v[222:225], v[130:133], v[34:49]
	v_mfma_f32_32x32x16_bf16 v[2:17], v[222:225], v[146:149], v[2:17]
	v_mfma_f32_32x32x16_bf16 v[34:49], v[234:237], v[134:137], v[34:49]
	v_mfma_f32_32x32x16_bf16 v[2:17], v[234:237], v[150:153], v[2:17]
	v_mfma_f32_32x32x16_bf16 v[34:49], v[238:241], v[138:141], v[34:49]
	v_mfma_f32_32x32x16_bf16 v[2:17], v[238:241], v[154:157], v[2:17]
	v_mfma_f32_32x32x16_bf16 v[34:49], v[242:245], v[142:145], v[34:49]
	v_mfma_f32_32x32x16_bf16 v[2:17], v[242:245], v[158:161], v[2:17]
	s_setprio 0
	s_barrier
	ds_read_b128 v[192:195], v250 offset:32768
	ds_read_b128 v[196:199], v251 offset:32768
	ds_read_b128 v[208:211], v252 offset:32768
	ds_read_b128 v[218:221], v233 offset:32768
	ds_read_b128 v[130:133], v246 offset:32768
	ds_read_b128 v[134:137], v247 offset:32768
	ds_read_b128 v[138:141], v248 offset:32768
	ds_read_b128 v[142:145], v249 offset:32768
	ds_read_b128 v[146:149], v246 offset:36864
	ds_read_b128 v[150:153], v247 offset:36864
	ds_read_b128 v[154:157], v248 offset:36864
	ds_read_b128 v[158:161], v249 offset:36864
	s_waitcnt vmcnt(2)
	s_barrier
	s_waitcnt lgkmcnt(0)
	s_setprio 1
	v_mfma_f32_32x32x16_bf16 v[114:129], v[192:195], v[130:133], v[114:129]
	v_mfma_f32_32x32x16_bf16 v[82:97], v[192:195], v[146:149], v[82:97]
	v_mfma_f32_32x32x16_bf16 v[114:129], v[196:199], v[134:137], v[114:129]
	v_mfma_f32_32x32x16_bf16 v[82:97], v[196:199], v[150:153], v[82:97]
	v_mfma_f32_32x32x16_bf16 v[114:129], v[208:211], v[138:141], v[114:129]
	v_mfma_f32_32x32x16_bf16 v[82:97], v[208:211], v[154:157], v[82:97]
	v_mfma_f32_32x32x16_bf16 v[114:129], v[218:221], v[142:145], v[114:129]
	v_mfma_f32_32x32x16_bf16 v[82:97], v[218:221], v[158:161], v[82:97]
	s_setprio 0
	s_barrier
	ds_read_b128 v[222:225], v250 offset:36864
	ds_read_b128 v[234:237], v251 offset:36864
	ds_read_b128 v[238:241], v252 offset:36864
	ds_read_b128 v[242:245], v233 offset:36864
	s_waitcnt vmcnt(0)
	s_barrier
	s_waitcnt lgkmcnt(0)
	s_setprio 1
	v_mfma_f32_32x32x16_bf16 v[98:113], v[222:225], v[130:133], v[98:113]
	v_mfma_f32_32x32x16_bf16 v[66:81], v[222:225], v[146:149], v[66:81]
	v_mfma_f32_32x32x16_bf16 v[98:113], v[234:237], v[134:137], v[98:113]
	v_mfma_f32_32x32x16_bf16 v[66:81], v[234:237], v[150:153], v[66:81]
	v_mfma_f32_32x32x16_bf16 v[98:113], v[238:241], v[138:141], v[98:113]
	v_mfma_f32_32x32x16_bf16 v[66:81], v[238:241], v[154:157], v[66:81]
	v_mfma_f32_32x32x16_bf16 v[98:113], v[242:245], v[142:145], v[98:113]
	v_mfma_f32_32x32x16_bf16 v[66:81], v[242:245], v[158:161], v[66:81]
	s_setprio 0
	s_barrier
	ds_read_b128 v[130:133], v246 offset:40960
	ds_read_b128 v[134:137], v247 offset:40960
	ds_read_b128 v[138:141], v248 offset:40960
	ds_read_b128 v[142:145], v249 offset:40960
	ds_read_b128 v[146:149], v246 offset:45056
	ds_read_b128 v[150:153], v247 offset:45056
	ds_read_b128 v[154:157], v248 offset:45056
	ds_read_b128 v[158:161], v249 offset:45056
	s_barrier
	s_waitcnt lgkmcnt(0)
	s_setprio 1
	v_mfma_f32_32x32x16_bf16 v[50:65], v[192:195], v[130:133], v[50:65]
	v_mfma_f32_32x32x16_bf16 v[18:33], v[192:195], v[146:149], v[18:33]
	v_mfma_f32_32x32x16_bf16 v[50:65], v[196:199], v[134:137], v[50:65]
	v_mfma_f32_32x32x16_bf16 v[18:33], v[196:199], v[150:153], v[18:33]
	v_mfma_f32_32x32x16_bf16 v[50:65], v[208:211], v[138:141], v[50:65]
	v_mfma_f32_32x32x16_bf16 v[18:33], v[208:211], v[154:157], v[18:33]
	v_mfma_f32_32x32x16_bf16 v[50:65], v[218:221], v[142:145], v[50:65]
	v_mfma_f32_32x32x16_bf16 v[18:33], v[218:221], v[158:161], v[18:33]
	s_setprio 0
	s_setprio 1
	v_mfma_f32_32x32x16_bf16 v[34:49], v[222:225], v[130:133], v[34:49]
	v_mfma_f32_32x32x16_bf16 v[2:17], v[222:225], v[146:149], v[2:17]
	v_mfma_f32_32x32x16_bf16 v[34:49], v[234:237], v[134:137], v[34:49]
	v_mfma_f32_32x32x16_bf16 v[2:17], v[234:237], v[150:153], v[2:17]
	v_mfma_f32_32x32x16_bf16 v[34:49], v[238:241], v[138:141], v[34:49]
	v_mfma_f32_32x32x16_bf16 v[2:17], v[238:241], v[154:157], v[2:17]
	v_mfma_f32_32x32x16_bf16 v[34:49], v[242:245], v[142:145], v[34:49]
	v_mfma_f32_32x32x16_bf16 v[2:17], v[242:245], v[158:161], v[2:17]
	s_setprio 0
	s_barrier
	v_readfirstlane_b32 s15, v200
	s_lshr_b32 s15, s15, 8
	s_cmp_lg_u32 s15, 0
	s_cbranch_scc1 .Lgou_nolag2
	s_barrier
.Lgou_nolag2:
	s_nop 15
	s_nop 15
	s_waitcnt lgkmcnt(3)
	s_waitcnt lgkmcnt(2)
	s_waitcnt lgkmcnt(1)
	s_waitcnt lgkmcnt(0)
	s_waitcnt lgkmcnt(0)
	s_waitcnt lgkmcnt(3)
	s_waitcnt lgkmcnt(2)
	s_waitcnt lgkmcnt(1)
	s_waitcnt lgkmcnt(0)
	s_waitcnt lgkmcnt(0)
	s_waitcnt lgkmcnt(3)
	s_waitcnt lgkmcnt(2)
	s_waitcnt lgkmcnt(1)
	s_waitcnt lgkmcnt(0)
	s_waitcnt lgkmcnt(0)
	v_add_u32_e32 v150, 0x12000, v170
	s_waitcnt lgkmcnt(3)
	s_waitcnt lgkmcnt(2)
	s_waitcnt lgkmcnt(1)
	s_waitcnt lgkmcnt(0)
	s_waitcnt lgkmcnt(0)
	s_waitcnt lgkmcnt(1)
	s_waitcnt lgkmcnt(0)
	s_waitcnt lgkmcnt(0)
	s_waitcnt lgkmcnt(3)
	s_waitcnt lgkmcnt(2)
	s_waitcnt lgkmcnt(1)
	s_waitcnt lgkmcnt(0)
	s_waitcnt lgkmcnt(0)
	s_waitcnt lgkmcnt(3)
	s_waitcnt lgkmcnt(2)
	s_waitcnt lgkmcnt(1)
	s_waitcnt lgkmcnt(0)
	s_waitcnt lgkmcnt(0)
	s_waitcnt lgkmcnt(0)
	s_add_i32 s0, s0, s46
	s_cmpk_gt_i32 s0, 0xff
	v_add_u32_e32 v132, s1, v182
	v_or_b32_e32 v130, s10, v173
	v_ashrrev_i32_e32 v133, 31, v132
	v_ashrrev_i32_e32 v131, 31, v130
	v_lshlrev_b64 v[130:131], 1, v[130:131]
	s_nop 3
	v_cvt_pk_bf16_f32 v114, v114, v115
	v_cvt_pk_bf16_f32 v115, v116, v117
	v_cvt_pk_bf16_f32 v98, v98, v99
	v_cvt_pk_bf16_f32 v99, v100, v101
	v_readlane_b32 s1, v254, 52
	s_nop 1
	v_add_u32_e32 v191, s1, v191
	s_nop 5
	v_cvt_pk_bf16_f32 v82, v82, v83
	v_lshlrev_b64 v[134:135], 11, v[132:133]
	v_lshl_add_u64 v[134:135], s[80:81], 0, v[134:135]
	v_lshl_add_u64 v[134:135], v[134:135], 0, v[130:131]
	v_lshl_add_u64 v[134:135], v[134:135], 0, v[0:1]
	global_store_dwordx2 v[134:135], v[98:99], off offset:64
	v_cvt_pk_bf16_f32 v98, v102, v103
	v_cvt_pk_bf16_f32 v99, v104, v105
	global_store_dwordx2 v[134:135], v[98:99], off offset:80
	v_cvt_pk_bf16_f32 v98, v106, v107
	v_cvt_pk_bf16_f32 v99, v108, v109
	global_store_dwordx2 v[134:135], v[98:99], off offset:96
	v_cvt_pk_bf16_f32 v98, v110, v111
	v_cvt_pk_bf16_f32 v99, v112, v113
	global_store_dwordx2 v[134:135], v[98:99], off offset:112
	v_or_b32_e32 v98, 32, v132
	v_ashrrev_i32_e32 v99, 31, v98
	v_lshlrev_b64 v[98:99], 11, v[98:99]
	v_lshl_add_u64 v[98:99], s[80:81], 0, v[98:99]
	v_lshl_add_u64 v[98:99], v[98:99], 0, v[130:131]
	v_lshl_add_u64 v[98:99], v[98:99], 0, v[0:1]
	v_cvt_pk_bf16_f32 v66, v66, v67
	v_cvt_pk_bf16_f32 v67, v68, v69
	global_store_dwordx2 v[98:99], v[66:67], off offset:64
	v_cvt_pk_bf16_f32 v66, v70, v71
	v_cvt_pk_bf16_f32 v67, v72, v73
	global_store_dwordx2 v[98:99], v[66:67], off offset:80
	v_cvt_pk_bf16_f32 v66, v74, v75
	v_cvt_pk_bf16_f32 v67, v76, v77
	global_store_dwordx2 v[98:99], v[66:67], off offset:96
	v_cvt_pk_bf16_f32 v66, v78, v79
	v_cvt_pk_bf16_f32 v67, v80, v81
	global_store_dwordx2 v[98:99], v[66:67], off offset:112
	v_or_b32_e32 v66, 64, v132
	v_ashrrev_i32_e32 v67, 31, v66
	v_lshlrev_b64 v[66:67], 11, v[66:67]
	v_lshl_add_u64 v[66:67], s[80:81], 0, v[66:67]
	v_lshl_add_u64 v[66:67], v[66:67], 0, v[130:131]
	v_lshl_add_u64 v[66:67], v[66:67], 0, v[0:1]
	v_cvt_pk_bf16_f32 v34, v34, v35
	v_cvt_pk_bf16_f32 v35, v36, v37
	global_store_dwordx2 v[66:67], v[34:35], off offset:64
	v_cvt_pk_bf16_f32 v34, v38, v39
	v_cvt_pk_bf16_f32 v35, v40, v41
	global_store_dwordx2 v[66:67], v[34:35], off offset:80
	v_cvt_pk_bf16_f32 v34, v42, v43
	v_cvt_pk_bf16_f32 v35, v44, v45
	global_store_dwordx2 v[66:67], v[34:35], off offset:96
	v_cvt_pk_bf16_f32 v34, v46, v47
	v_cvt_pk_bf16_f32 v35, v48, v49
	global_store_dwordx2 v[66:67], v[34:35], off offset:112
	v_or_b32_e32 v34, 0x60, v132
	v_ashrrev_i32_e32 v35, 31, v34
	v_lshlrev_b64 v[34:35], 11, v[34:35]
	v_lshl_add_u64 v[34:35], s[80:81], 0, v[34:35]
	v_lshl_add_u64 v[34:35], v[34:35], 0, v[130:131]
	v_cvt_pk_bf16_f32 v83, v84, v85
	v_cvt_pk_bf16_f32 v50, v50, v51
	v_cvt_pk_bf16_f32 v51, v52, v53
	v_lshl_add_u64 v[34:35], v[34:35], 0, v[0:1]
	v_cvt_pk_bf16_f32 v18, v18, v19
	v_cvt_pk_bf16_f32 v19, v20, v21
	s_nop 4
	v_cvt_pk_bf16_f32 v2, v2, v3
	v_cvt_pk_bf16_f32 v3, v4, v5
	global_store_dwordx2 v[134:135], v[114:115], off
	v_cvt_pk_bf16_f32 v114, v118, v119
	v_cvt_pk_bf16_f32 v115, v120, v121
	global_store_dwordx2 v[98:99], v[82:83], off
	v_cvt_pk_bf16_f32 v82, v86, v87
	v_cvt_pk_bf16_f32 v83, v88, v89
	global_store_dwordx2 v[66:67], v[50:51], off
	v_cvt_pk_bf16_f32 v50, v54, v55
	v_cvt_pk_bf16_f32 v51, v56, v57
	global_store_dwordx2 v[34:35], v[18:19], off
	v_cvt_pk_bf16_f32 v18, v22, v23
	v_cvt_pk_bf16_f32 v19, v24, v25
	global_store_dwordx2 v[34:35], v[2:3], off offset:64
	v_cvt_pk_bf16_f32 v2, v6, v7
	v_cvt_pk_bf16_f32 v3, v8, v9
	global_store_dwordx2 v[134:135], v[114:115], off offset:16
	v_cvt_pk_bf16_f32 v114, v122, v123
	v_cvt_pk_bf16_f32 v115, v124, v125
	global_store_dwordx2 v[98:99], v[82:83], off offset:16
	v_cvt_pk_bf16_f32 v82, v90, v91
	v_cvt_pk_bf16_f32 v83, v92, v93
	global_store_dwordx2 v[66:67], v[50:51], off offset:16
	v_cvt_pk_bf16_f32 v50, v58, v59
	v_cvt_pk_bf16_f32 v51, v60, v61
	global_store_dwordx2 v[34:35], v[18:19], off offset:16
	v_cvt_pk_bf16_f32 v18, v26, v27
	v_cvt_pk_bf16_f32 v19, v28, v29
	global_store_dwordx2 v[34:35], v[2:3], off offset:80
	v_cvt_pk_bf16_f32 v2, v10, v11
	v_cvt_pk_bf16_f32 v3, v12, v13
	global_store_dwordx2 v[134:135], v[114:115], off offset:32
	v_cvt_pk_bf16_f32 v114, v126, v127
	v_cvt_pk_bf16_f32 v115, v128, v129
	global_store_dwordx2 v[98:99], v[82:83], off offset:32
	v_cvt_pk_bf16_f32 v82, v94, v95
	v_cvt_pk_bf16_f32 v83, v96, v97
	global_store_dwordx2 v[66:67], v[50:51], off offset:32
	v_cvt_pk_bf16_f32 v50, v62, v63
	v_cvt_pk_bf16_f32 v51, v64, v65
	global_store_dwordx2 v[34:35], v[18:19], off offset:32
	v_cvt_pk_bf16_f32 v18, v30, v31
	v_cvt_pk_bf16_f32 v19, v32, v33
	global_store_dwordx2 v[34:35], v[2:3], off offset:96
	v_cvt_pk_bf16_f32 v2, v14, v15
	v_cvt_pk_bf16_f32 v3, v16, v17
	global_store_dwordx2 v[134:135], v[114:115], off offset:48
	global_store_dwordx2 v[98:99], v[82:83], off offset:48
	global_store_dwordx2 v[66:67], v[50:51], off offset:48
	global_store_dwordx2 v[34:35], v[18:19], off offset:48
	global_store_dwordx2 v[34:35], v[2:3], off offset:112
	s_cbranch_scc0 .LBB0_72

.LBB0_215:
	s_mul_hi_i32 s0, s10, 0x92492493
	s_add_i32 s0, s0, s10
	s_lshr_b32 s1, s0, 31
	s_ashr_i32 s0, s0, 5
	s_add_i32 s13, s0, s1
	s_lshl_b32 s0, s13, 3
	s_sub_i32 s1, 0x42, s0
	s_min_u32 s1, s1, 8
	v_cvt_f32_ubyte0_e32 v0, s1
	v_rcp_iflag_f32_e32 v0, v0
	s_sub_i32 s14, 0, s1
	s_mul_i32 s2, s13, 0xffffffc8
	s_add_i32 s2, s2, s10
	v_mul_f32_e32 v0, 0x4f7ffffe, v0
	v_cvt_u32_f32_e32 v0, v0
	s_abs_i32 s12, s2
	s_ashr_i32 s3, s2, 31
	s_mul_i32 s13, s13, 48
	v_readfirstlane_b32 s15, v0
	s_mul_i32 s14, s14, s15
	s_mul_hi_u32 s14, s15, s14
	s_add_i32 s15, s15, s14
	s_mul_hi_u32 s14, s12, s15
	s_mul_i32 s15, s14, s1
	s_sub_i32 s12, s12, s15
	s_add_i32 s15, s14, 1
	s_sub_i32 s16, s12, s1
	s_cmp_ge_u32 s12, s1
	s_cselect_b32 s14, s15, s14
	s_cselect_b32 s12, s16, s12
	s_add_i32 s15, s14, 1
	s_cmp_ge_u32 s12, s1
	s_cselect_b32 s12, s15, s14
	s_xor_b32 s12, s12, s3
	s_sub_i32 s3, s12, s3
	s_mul_i32 s14, s3, s1
	s_add_i32 s2, s2, s0
	s_sub_i32 s0, s2, s14
	s_lshl_b32 s1, s0, 8
	v_add_u32_e32 v2, s1, v164
	v_ashrrev_i32_e32 v3, 31, v2
	v_lshlrev_b64 v[2:3], 11, v[2:3]
	s_lshl_b32 s0, s3, 8
	v_lshl_add_u64 v[50:51], v[168:169], 0, v[2:3]
	v_add_u32_e32 v4, s0, v164
	v_add_co_u32_e32 v52, vcc, s7, v50
	v_ashrrev_i32_e32 v5, 31, v4
	s_nop 0
	v_addc_co_u32_e32 v53, vcc, 0, v51, vcc
	v_lshlrev_b64 v[46:47], 11, v[4:5]
	v_add_co_u32_e32 v54, vcc, s8, v50
	v_lshl_add_u64 v[48:49], v[166:167], 0, v[46:47]
	s_nop 0
	v_addc_co_u32_e32 v55, vcc, 0, v51, vcc
	v_add_co_u32_e32 v56, vcc, s7, v48
	v_addc_co_u32_e32 v57, vcc, 0, v49, vcc
	v_add_co_u32_e32 v58, vcc, s8, v48
	v_addc_co_u32_e32 v59, vcc, 0, v49, vcc
	v_add_co_u32_e32 v60, vcc, s9, v48
	v_addc_co_u32_e32 v61, vcc, 0, v49, vcc
	v_add_co_u32_e32 v62, vcc, s9, v50
	v_addc_co_u32_e32 v63, vcc, 0, v51, vcc
	s_sub_i32 s14, s10, s14
	s_sub_i32 s13, s14, s13
	s_lshl_b32 s14, s13, 8
	s_ashr_i32 s15, s14, 31
	v_lshl_add_u64 v[196:197], v[192:193], 0, v[46:47]
	v_lshl_add_u64 v[46:47], v[164:165], 0, s[14:15]
	v_mov_b32_e32 v2, 0
	v_lshlrev_b64 v[46:47], 11, v[46:47]
	s_mov_b32 s12, 1
	s_mov_b64 s[2:3], 0
	v_mov_b32_e32 v3, v2
	v_mov_b32_e32 v4, v2
	v_mov_b32_e32 v5, v2
	v_mov_b32_e32 v6, v2
	v_mov_b32_e32 v7, v2
	v_mov_b32_e32 v8, v2
	v_mov_b32_e32 v9, v2
	v_mov_b32_e32 v10, v2
	v_mov_b32_e32 v11, v2
	v_mov_b32_e32 v12, v2
	v_mov_b32_e32 v13, v2
	v_lshl_add_u64 v[198:199], v[194:195], 0, v[46:47]
	v_mov_b32_e32 v46, v2
	v_mov_b32_e32 v47, v2
	v_mov_b32_e32 v48, v2
	v_mov_b32_e32 v49, v2
	v_mov_b32_e32 v50, v2
	v_mov_b32_e32 v51, v2
	v_mov_b32_e32 v52, v2
	v_mov_b32_e32 v53, v2
	v_mov_b32_e32 v54, v2
	v_mov_b32_e32 v55, v2
	v_mov_b32_e32 v56, v2
	v_mov_b32_e32 v57, v2
	v_mov_b32_e32 v58, v2
	v_mov_b32_e32 v59, v2
	v_mov_b32_e32 v60, v2
	v_mov_b32_e32 v61, v2
	v_mov_b32_e32 v62, v2
	v_mov_b32_e32 v63, v2
	v_mov_b32_e32 v64, v2
	v_mov_b32_e32 v65, v2
	v_mov_b32_e32 v66, v2
	v_mov_b32_e32 v14, v2
	v_mov_b32_e32 v15, v2
	v_mov_b32_e32 v16, v2
	v_mov_b32_e32 v17, v2
	v_mov_b32_e32 v34, v2
	v_mov_b32_e32 v35, v2
	v_mov_b32_e32 v36, v2
	v_mov_b32_e32 v37, v2
	v_mov_b32_e32 v38, v2
	v_mov_b32_e32 v39, v2
	v_mov_b32_e32 v40, v2
	v_mov_b32_e32 v41, v2
	v_mov_b32_e32 v42, v2
	v_mov_b32_e32 v43, v2
	v_mov_b32_e32 v44, v2
	v_mov_b32_e32 v45, v2
	v_mov_b32_e32 v18, v2
	v_mov_b32_e32 v19, v2
	v_mov_b32_e32 v20, v2
	v_mov_b32_e32 v21, v2
	v_mov_b32_e32 v22, v2
	v_mov_b32_e32 v23, v2
	v_mov_b32_e32 v24, v2
	v_mov_b32_e32 v25, v2
	v_mov_b32_e32 v26, v2
	v_mov_b32_e32 v27, v2
	v_mov_b32_e32 v28, v2
	v_mov_b32_e32 v29, v2
	v_mov_b32_e32 v30, v2
	v_mov_b32_e32 v31, v2
	v_mov_b32_e32 v32, v2
	v_mov_b32_e32 v33, v2
	v_mov_b32_e32 v67, v2
	v_mov_b32_e32 v68, v2
	v_mov_b32_e32 v69, v2
	v_mov_b32_e32 v70, v2
	v_mov_b32_e32 v71, v2
	v_mov_b32_e32 v72, v2
	v_mov_b32_e32 v73, v2
	v_mov_b32_e32 v74, v2
	v_mov_b32_e32 v75, v2
	v_mov_b32_e32 v76, v2
	v_mov_b32_e32 v77, v2
	v_mov_b32_e32 v78, v2
	v_mov_b32_e32 v79, v2
	v_mov_b32_e32 v80, v2
	v_mov_b32_e32 v81, v2
	v_mov_b32_e32 v98, v2
	v_mov_b32_e32 v99, v2
	v_mov_b32_e32 v100, v2
	v_mov_b32_e32 v101, v2
	v_mov_b32_e32 v102, v2
	v_mov_b32_e32 v103, v2
	v_mov_b32_e32 v104, v2
	v_mov_b32_e32 v105, v2
	v_mov_b32_e32 v106, v2
	v_mov_b32_e32 v107, v2
	v_mov_b32_e32 v108, v2
	v_mov_b32_e32 v109, v2
	v_mov_b32_e32 v110, v2
	v_mov_b32_e32 v111, v2
	v_mov_b32_e32 v112, v2
	v_mov_b32_e32 v113, v2
	v_mov_b32_e32 v82, v2
	v_mov_b32_e32 v83, v2
	v_mov_b32_e32 v84, v2
	v_mov_b32_e32 v85, v2
	v_mov_b32_e32 v86, v2
	v_mov_b32_e32 v87, v2
	v_mov_b32_e32 v88, v2
	v_mov_b32_e32 v89, v2
	v_mov_b32_e32 v90, v2
	v_mov_b32_e32 v91, v2
	v_mov_b32_e32 v92, v2
	v_mov_b32_e32 v93, v2
	v_mov_b32_e32 v94, v2
	v_mov_b32_e32 v95, v2
	v_mov_b32_e32 v96, v2
	v_mov_b32_e32 v97, v2
	v_mov_b32_e32 v114, v2
	v_mov_b32_e32 v115, v2
	v_mov_b32_e32 v116, v2
	v_mov_b32_e32 v117, v2
	v_mov_b32_e32 v118, v2
	v_mov_b32_e32 v119, v2
	v_mov_b32_e32 v120, v2
	v_mov_b32_e32 v121, v2
	v_mov_b32_e32 v122, v2
	v_mov_b32_e32 v123, v2
	v_mov_b32_e32 v124, v2
	v_mov_b32_e32 v125, v2
	v_mov_b32_e32 v126, v2
	v_mov_b32_e32 v127, v2
	v_mov_b32_e32 v128, v2
	v_mov_b32_e32 v129, v2
	s_waitcnt lgkmcnt(0)
	v_lshrrev_b32_e32 v130, 6, v200
	v_and_b32_e32 v131, 63, v200
	v_readfirstlane_b32 s41, v130
	s_lshr_b32 s16, s41, 2
	s_lshl_b32 s16, s16, 7
	s_and_b32 s42, s41, 3
	s_lshl_b32 s42, s42, 4
	s_add_u32 s16, s16, s42
	s_add_u32 s42, s16, s1
	s_mul_i32 s42, s42, 2048
	s_add_u32 s2, s36, 0x308d800
	s_addc_u32 s3, s37, 0
	s_add_u32 s2, s2, s42
	s_addc_u32 s3, s3, 0
	s_lshl_b32 s16, s16, 7
	s_lshr_b32 s40, s41, 1
	s_lshl_b32 s40, s40, 6
	s_and_b32 s42, s41, 1
	s_lshl_b32 s42, s42, 4
	s_add_u32 s40, s40, s42
	v_readlane_b32 s15, v255, 30
	s_nop 3
	s_mul_i32 s15, s15, 0x400000
	s_add_u32 s14, s36, s15
	s_addc_u32 s15, s37, 0
	s_add_u32 s14, s14, 0x6d800
	s_addc_u32 s15, s15, 0
	s_add_u32 s42, s40, s0
	s_mul_i32 s42, s42, 2048
	s_add_u32 s14, s14, s42
	s_addc_u32 s15, s15, 0
	s_lshl_b32 s40, s40, 7
	s_add_u32 s40, s40, 0x10000
	s_add_u32 s12, s2, 0x20000
	s_addc_u32 s13, s3, 0
	s_add_u32 s22, s14, 0x10000
	s_addc_u32 s23, s15, 0
	v_lshrrev_b32_e32 v132, 3, v131
	v_and_b32_e32 v133, 7, v131
	v_lshrrev_b32_e32 v134, 4, v131
	v_xor_b32_e32 v133, v133, v134
	v_lshlrev_b32_e32 v133, 4, v133
	v_mul_u32_u24_e32 v134, 2048, v132
	v_or_b32_e32 v227, v134, v133
	v_add_u32_e32 v228, 16384, v227
	v_xor_b32_e32 v228, 64, v228
	v_and_b32_e32 v132, 31, v131
	v_lshrrev_b32_e32 v133, 5, v131
	v_bfe_u32 v134, v132, 1, 3
	v_and_b32_e32 v135, 1, v134
	v_xor_b32_e32 v133, v133, v135
	v_lshlrev_b32_e32 v133, 4, v133
	v_lshl_add_u32 v133, v132, 7, v133
	v_and_b32_e32 v134, 6, v134
	s_lshr_b32 s42, s41, 2
	s_lshl_b32 s42, s42, 14
	v_xor_b32_e32 v135, 0, v134
	v_lshl_add_u32 v135, v135, 4, v133
	v_add_u32_e32 v192, s42, v135
	v_xor_b32_e32 v135, 2, v134
	v_lshl_add_u32 v135, v135, 4, v133
	v_add_u32_e32 v193, s42, v135
	v_xor_b32_e32 v135, 4, v134
	v_lshl_add_u32 v135, v135, 4, v133
	v_add_u32_e32 v194, s42, v135
	v_xor_b32_e32 v135, 6, v134
	v_lshl_add_u32 v135, v135, 4, v133
	v_add_u32_e32 v195, s42, v135
	s_and_b32 s42, s41, 3
	s_lshl_b32 s42, s42, 13
	s_add_u32 s42, s42, 0x10000
	v_xor_b32_e32 v135, 0, v134
	v_lshl_add_u32 v135, v135, 4, v133
	v_add_u32_e32 v203, s42, v135
	v_xor_b32_e32 v135, 2, v134
	v_lshl_add_u32 v135, v135, 4, v133
	v_add_u32_e32 v204, s42, v135
	v_xor_b32_e32 v135, 4, v134
	v_lshl_add_u32 v135, v135, 4, v133
	v_add_u32_e32 v214, s42, v135
	v_xor_b32_e32 v135, 6, v134
	v_lshl_add_u32 v135, v135, 4, v133
	v_add_u32_e32 v226, s42, v135
	s_add_u32 m0, s40, 0x0
	s_nop 0
	global_load_lds_dwordx4 v227, s[14:15]
	s_add_u32 m0, s40, 0x400
	s_nop 0
	global_load_lds_dwordx4 v228, s[14:15]
	s_add_u32 s14, s14, 0x80
	s_addc_u32 s15, s15, 0
	s_add_u32 m0, s16, 0x0
	s_nop 0
	global_load_lds_dwordx4 v227, s[2:3]
	s_add_u32 m0, s16, 0x400
	s_nop 0
	global_load_lds_dwordx4 v228, s[2:3]
	s_add_u32 s2, s2, 0x80
	s_addc_u32 s3, s3, 0
	s_add_u32 m0, s40, 0x1000
	s_nop 0
	global_load_lds_dwordx4 v227, s[22:23]
	s_add_u32 m0, s40, 0x1400
	s_nop 0
	global_load_lds_dwordx4 v228, s[22:23]
	s_add_u32 s22, s22, 0x80
	s_addc_u32 s23, s23, 0
	s_add_u32 m0, s16, 0x2000
	s_nop 0
	global_load_lds_dwordx4 v227, s[12:13]
	s_add_u32 m0, s16, 0x2400
	s_nop 0
	global_load_lds_dwordx4 v228, s[12:13]
	s_add_u32 s12, s12, 0x80
	s_addc_u32 s13, s13, 0
	v_readfirstlane_b32 s42, v200
	s_lshr_b32 s42, s42, 8
	s_cmp_lg_u32 s42, 0
	s_cbranch_scc0 .Lgin_nolag
	s_barrier
.Lgin_nolag:
	s_waitcnt vmcnt(4)
	s_barrier
	s_add_u32 m0, s40, 0x8000
	s_nop 0
	global_load_lds_dwordx4 v227, s[14:15]
	s_add_u32 m0, s40, 0x8400
	s_nop 0
	global_load_lds_dwordx4 v228, s[14:15]
	s_add_u32 s14, s14, 0x80
	s_addc_u32 s15, s15, 0
	s_add_u32 m0, s16, 0x8000
	s_nop 0
	global_load_lds_dwordx4 v227, s[2:3]
	s_add_u32 m0, s16, 0x8400
	s_nop 0
	global_load_lds_dwordx4 v228, s[2:3]
	s_add_u32 s2, s2, 0x80
	s_addc_u32 s3, s3, 0
	s_add_u32 m0, s40, 0x9000
	s_nop 0
	global_load_lds_dwordx4 v227, s[22:23]
	s_add_u32 m0, s40, 0x9400
	s_nop 0
	global_load_lds_dwordx4 v228, s[22:23]
	s_add_u32 s22, s22, 0x80
	s_addc_u32 s23, s23, 0
	s_waitcnt vmcnt(6)
	s_barrier
	s_mov_b32 s41, 0
.Lgin_loop:
	ds_read_b128 v[196:199], v203
	ds_read_b128 v[208:211], v204
	ds_read_b128 v[218:221], v214
	ds_read_b128 v[222:225], v226
	ds_read_b128 v[130:133], v192 offset:0
	ds_read_b128 v[134:137], v193 offset:0
	ds_read_b128 v[138:141], v194 offset:0
	ds_read_b128 v[142:145], v195 offset:0
	ds_read_b128 v[146:149], v192 offset:4096
	ds_read_b128 v[150:153], v193 offset:4096
	ds_read_b128 v[154:157], v194 offset:4096
	ds_read_b128 v[158:161], v195 offset:4096
	s_add_u32 m0, s16, 0xa000
	s_nop 0
	global_load_lds_dwordx4 v227, s[12:13]
	s_add_u32 m0, s16, 0xa400
	s_nop 0
	global_load_lds_dwordx4 v228, s[12:13]
	s_add_u32 s12, s12, 0x80
	s_addc_u32 s13, s13, 0
	s_waitcnt lgkmcnt(8)
	s_barrier
	s_waitcnt lgkmcnt(0)
	s_setprio 1
	v_mfma_f32_32x32x16_bf16 v[114:129], v[196:199], v[130:133], v[114:129]
	v_mfma_f32_32x32x16_bf16 v[82:97], v[196:199], v[146:149], v[82:97]
	v_mfma_f32_32x32x16_bf16 v[114:129], v[208:211], v[134:137], v[114:129]
	v_mfma_f32_32x32x16_bf16 v[82:97], v[208:211], v[150:153], v[82:97]
	v_mfma_f32_32x32x16_bf16 v[114:129], v[218:221], v[138:141], v[114:129]
	v_mfma_f32_32x32x16_bf16 v[82:97], v[218:221], v[154:157], v[82:97]
	v_mfma_f32_32x32x16_bf16 v[114:129], v[222:225], v[142:145], v[114:129]
	v_mfma_f32_32x32x16_bf16 v[82:97], v[222:225], v[158:161], v[82:97]
	s_setprio 0
	s_barrier
	ds_read_b128 v[236:239], v203 offset:4096
	ds_read_b128 v[240:243], v204 offset:4096
	ds_read_b128 v[244:247], v214 offset:4096
	ds_read_b128 v[248:251], v226 offset:4096
	s_add_u32 m0, s40, 0x0
	s_nop 0
	global_load_lds_dwordx4 v227, s[14:15]
	s_add_u32 m0, s40, 0x400
	s_nop 0
	global_load_lds_dwordx4 v228, s[14:15]
	s_add_u32 s14, s14, 0x80
	s_addc_u32 s15, s15, 0
	s_barrier
	s_waitcnt lgkmcnt(0)
	s_setprio 1
	v_mfma_f32_32x32x16_bf16 v[98:113], v[236:239], v[130:133], v[98:113]
	v_mfma_f32_32x32x16_bf16 v[66:81], v[236:239], v[146:149], v[66:81]
	v_mfma_f32_32x32x16_bf16 v[98:113], v[240:243], v[134:137], v[98:113]
	v_mfma_f32_32x32x16_bf16 v[66:81], v[240:243], v[150:153], v[66:81]
	v_mfma_f32_32x32x16_bf16 v[98:113], v[244:247], v[138:141], v[98:113]
	v_mfma_f32_32x32x16_bf16 v[66:81], v[244:247], v[154:157], v[66:81]
	v_mfma_f32_32x32x16_bf16 v[98:113], v[248:251], v[142:145], v[98:113]
	v_mfma_f32_32x32x16_bf16 v[66:81], v[248:251], v[158:161], v[66:81]
	s_setprio 0
	s_barrier
	ds_read_b128 v[130:133], v192 offset:8192
	ds_read_b128 v[134:137], v193 offset:8192
	ds_read_b128 v[138:141], v194 offset:8192
	ds_read_b128 v[142:145], v195 offset:8192
	ds_read_b128 v[146:149], v192 offset:12288
	ds_read_b128 v[150:153], v193 offset:12288
	ds_read_b128 v[154:157], v194 offset:12288
	ds_read_b128 v[158:161], v195 offset:12288
	s_add_u32 m0, s16, 0x0
	s_nop 0
	global_load_lds_dwordx4 v227, s[2:3]
	s_add_u32 m0, s16, 0x400
	s_nop 0
	global_load_lds_dwordx4 v228, s[2:3]
	s_add_u32 s2, s2, 0x80
	s_addc_u32 s3, s3, 0
	s_barrier
	s_waitcnt lgkmcnt(0)
	s_setprio 1
	v_mfma_f32_32x32x16_bf16 v[50:65], v[196:199], v[130:133], v[50:65]
	v_mfma_f32_32x32x16_bf16 v[18:33], v[196:199], v[146:149], v[18:33]
	v_mfma_f32_32x32x16_bf16 v[50:65], v[208:211], v[134:137], v[50:65]
	v_mfma_f32_32x32x16_bf16 v[18:33], v[208:211], v[150:153], v[18:33]
	v_mfma_f32_32x32x16_bf16 v[50:65], v[218:221], v[138:141], v[50:65]
	v_mfma_f32_32x32x16_bf16 v[18:33], v[218:221], v[154:157], v[18:33]
	v_mfma_f32_32x32x16_bf16 v[50:65], v[222:225], v[142:145], v[50:65]
	v_mfma_f32_32x32x16_bf16 v[18:33], v[222:225], v[158:161], v[18:33]
	s_setprio 0
	s_barrier
	s_add_u32 m0, s40, 0x1000
	s_nop 0
	global_load_lds_dwordx4 v227, s[22:23]
	s_add_u32 m0, s40, 0x1400
	s_nop 0
	global_load_lds_dwordx4 v228, s[22:23]
	s_add_u32 s22, s22, 0x80
	s_addc_u32 s23, s23, 0
	s_waitcnt vmcnt(6)
	s_barrier
	s_setprio 1
	v_mfma_f32_32x32x16_bf16 v[34:49], v[236:239], v[130:133], v[34:49]
	v_mfma_f32_32x32x16_bf16 v[2:17], v[236:239], v[146:149], v[2:17]
	v_mfma_f32_32x32x16_bf16 v[34:49], v[240:243], v[134:137], v[34:49]
	v_mfma_f32_32x32x16_bf16 v[2:17], v[240:243], v[150:153], v[2:17]
	v_mfma_f32_32x32x16_bf16 v[34:49], v[244:247], v[138:141], v[34:49]
	v_mfma_f32_32x32x16_bf16 v[2:17], v[244:247], v[154:157], v[2:17]
	v_mfma_f32_32x32x16_bf16 v[34:49], v[248:251], v[142:145], v[34:49]
	v_mfma_f32_32x32x16_bf16 v[2:17], v[248:251], v[158:161], v[2:17]
	s_setprio 0
	s_barrier
	ds_read_b128 v[196:199], v203 offset:32768
	ds_read_b128 v[208:211], v204 offset:32768
	ds_read_b128 v[218:221], v214 offset:32768
	ds_read_b128 v[222:225], v226 offset:32768
	ds_read_b128 v[130:133], v192 offset:32768
	ds_read_b128 v[134:137], v193 offset:32768
	ds_read_b128 v[138:141], v194 offset:32768
	ds_read_b128 v[142:145], v195 offset:32768
	ds_read_b128 v[146:149], v192 offset:36864
	ds_read_b128 v[150:153], v193 offset:36864
	ds_read_b128 v[154:157], v194 offset:36864
	ds_read_b128 v[158:161], v195 offset:36864
	s_add_u32 m0, s16, 0x2000
	s_nop 0
	global_load_lds_dwordx4 v227, s[12:13]
	s_add_u32 m0, s16, 0x2400
	s_nop 0
	global_load_lds_dwordx4 v228, s[12:13]
	s_add_u32 s12, s12, 0x80
	s_addc_u32 s13, s13, 0
	s_waitcnt lgkmcnt(8)
	s_barrier
	s_waitcnt lgkmcnt(0)
	s_setprio 1
	v_mfma_f32_32x32x16_bf16 v[114:129], v[196:199], v[130:133], v[114:129]
	v_mfma_f32_32x32x16_bf16 v[82:97], v[196:199], v[146:149], v[82:97]
	v_mfma_f32_32x32x16_bf16 v[114:129], v[208:211], v[134:137], v[114:129]
	v_mfma_f32_32x32x16_bf16 v[82:97], v[208:211], v[150:153], v[82:97]
	v_mfma_f32_32x32x16_bf16 v[114:129], v[218:221], v[138:141], v[114:129]
	v_mfma_f32_32x32x16_bf16 v[82:97], v[218:221], v[154:157], v[82:97]
	v_mfma_f32_32x32x16_bf16 v[114:129], v[222:225], v[142:145], v[114:129]
	v_mfma_f32_32x32x16_bf16 v[82:97], v[222:225], v[158:161], v[82:97]
	s_setprio 0
	s_barrier
	ds_read_b128 v[236:239], v203 offset:36864
	ds_read_b128 v[240:243], v204 offset:36864
	ds_read_b128 v[244:247], v214 offset:36864
	ds_read_b128 v[248:251], v226 offset:36864
	s_add_u32 m0, s40, 0x8000
	s_nop 0
	global_load_lds_dwordx4 v227, s[14:15]
	s_add_u32 m0, s40, 0x8400
	s_nop 0
	global_load_lds_dwordx4 v228, s[14:15]
	s_add_u32 s14, s14, 0x80
	s_addc_u32 s15, s15, 0
	s_barrier
	s_waitcnt lgkmcnt(0)
	s_setprio 1
	v_mfma_f32_32x32x16_bf16 v[98:113], v[236:239], v[130:133], v[98:113]
	v_mfma_f32_32x32x16_bf16 v[66:81], v[236:239], v[146:149], v[66:81]
	v_mfma_f32_32x32x16_bf16 v[98:113], v[240:243], v[134:137], v[98:113]
	v_mfma_f32_32x32x16_bf16 v[66:81], v[240:243], v[150:153], v[66:81]
	v_mfma_f32_32x32x16_bf16 v[98:113], v[244:247], v[138:141], v[98:113]
	v_mfma_f32_32x32x16_bf16 v[66:81], v[244:247], v[154:157], v[66:81]
	v_mfma_f32_32x32x16_bf16 v[98:113], v[248:251], v[142:145], v[98:113]
	v_mfma_f32_32x32x16_bf16 v[66:81], v[248:251], v[158:161], v[66:81]
	s_setprio 0
	s_barrier
	ds_read_b128 v[130:133], v192 offset:40960
	ds_read_b128 v[134:137], v193 offset:40960
	ds_read_b128 v[138:141], v194 offset:40960
	ds_read_b128 v[142:145], v195 offset:40960
	ds_read_b128 v[146:149], v192 offset:45056
	ds_read_b128 v[150:153], v193 offset:45056
	ds_read_b128 v[154:157], v194 offset:45056
	ds_read_b128 v[158:161], v195 offset:45056
	s_add_u32 m0, s16, 0x8000
	s_nop 0
	global_load_lds_dwordx4 v227, s[2:3]
	s_add_u32 m0, s16, 0x8400
	s_nop 0
	global_load_lds_dwordx4 v228, s[2:3]
	s_add_u32 s2, s2, 0x80
	s_addc_u32 s3, s3, 0
	s_barrier
	s_waitcnt lgkmcnt(0)
	s_setprio 1
	v_mfma_f32_32x32x16_bf16 v[50:65], v[196:199], v[130:133], v[50:65]
	v_mfma_f32_32x32x16_bf16 v[18:33], v[196:199], v[146:149], v[18:33]
	v_mfma_f32_32x32x16_bf16 v[50:65], v[208:211], v[134:137], v[50:65]
	v_mfma_f32_32x32x16_bf16 v[18:33], v[208:211], v[150:153], v[18:33]
	v_mfma_f32_32x32x16_bf16 v[50:65], v[218:221], v[138:141], v[50:65]
	v_mfma_f32_32x32x16_bf16 v[18:33], v[218:221], v[154:157], v[18:33]
	v_mfma_f32_32x32x16_bf16 v[50:65], v[222:225], v[142:145], v[50:65]
	v_mfma_f32_32x32x16_bf16 v[18:33], v[222:225], v[158:161], v[18:33]
	s_setprio 0
	s_barrier
	s_add_u32 m0, s40, 0x9000
	s_nop 0
	global_load_lds_dwordx4 v227, s[22:23]
	s_add_u32 m0, s40, 0x9400
	s_nop 0
	global_load_lds_dwordx4 v228, s[22:23]
	s_add_u32 s22, s22, 0x80
	s_addc_u32 s23, s23, 0
	s_waitcnt vmcnt(6)
	s_barrier
	s_setprio 1
	v_mfma_f32_32x32x16_bf16 v[34:49], v[236:239], v[130:133], v[34:49]
	v_mfma_f32_32x32x16_bf16 v[2:17], v[236:239], v[146:149], v[2:17]
	v_mfma_f32_32x32x16_bf16 v[34:49], v[240:243], v[134:137], v[34:49]
	v_mfma_f32_32x32x16_bf16 v[2:17], v[240:243], v[150:153], v[2:17]
	v_mfma_f32_32x32x16_bf16 v[34:49], v[244:247], v[138:141], v[34:49]
	v_mfma_f32_32x32x16_bf16 v[2:17], v[244:247], v[154:157], v[2:17]
	v_mfma_f32_32x32x16_bf16 v[34:49], v[248:251], v[142:145], v[34:49]
	v_mfma_f32_32x32x16_bf16 v[2:17], v[248:251], v[158:161], v[2:17]
	s_setprio 0
	s_barrier
	s_add_i32 s41, s41, 2
	s_cmp_lt_u32 s41, 14
	s_cbranch_scc1 .Lgin_loop
	ds_read_b128 v[196:199], v203
	ds_read_b128 v[208:211], v204
	ds_read_b128 v[218:221], v214
	ds_read_b128 v[222:225], v226
	ds_read_b128 v[130:133], v192 offset:0
	ds_read_b128 v[134:137], v193 offset:0
	ds_read_b128 v[138:141], v194 offset:0
	ds_read_b128 v[142:145], v195 offset:0
	ds_read_b128 v[146:149], v192 offset:4096
	ds_read_b128 v[150:153], v193 offset:4096
	ds_read_b128 v[154:157], v194 offset:4096
	ds_read_b128 v[158:161], v195 offset:4096
	s_add_u32 m0, s16, 0xa000
	s_nop 0
	global_load_lds_dwordx4 v227, s[12:13]
	s_add_u32 m0, s16, 0xa400
	s_nop 0
	global_load_lds_dwordx4 v228, s[12:13]
	s_add_u32 s12, s12, 0x80
	s_addc_u32 s13, s13, 0
	s_barrier
	s_waitcnt lgkmcnt(0)
	s_setprio 1
	v_mfma_f32_32x32x16_bf16 v[114:129], v[196:199], v[130:133], v[114:129]
	v_mfma_f32_32x32x16_bf16 v[82:97], v[196:199], v[146:149], v[82:97]
	v_mfma_f32_32x32x16_bf16 v[114:129], v[208:211], v[134:137], v[114:129]
	v_mfma_f32_32x32x16_bf16 v[82:97], v[208:211], v[150:153], v[82:97]
	v_mfma_f32_32x32x16_bf16 v[114:129], v[218:221], v[138:141], v[114:129]
	v_mfma_f32_32x32x16_bf16 v[82:97], v[218:221], v[154:157], v[82:97]
	v_mfma_f32_32x32x16_bf16 v[114:129], v[222:225], v[142:145], v[114:129]
	v_mfma_f32_32x32x16_bf16 v[82:97], v[222:225], v[158:161], v[82:97]
	s_setprio 0
	s_barrier
	ds_read_b128 v[236:239], v203 offset:4096
	ds_read_b128 v[240:243], v204 offset:4096
	ds_read_b128 v[244:247], v214 offset:4096
	ds_read_b128 v[248:251], v226 offset:4096
	s_barrier
	s_waitcnt lgkmcnt(0)
	s_setprio 1
	v_mfma_f32_32x32x16_bf16 v[98:113], v[236:239], v[130:133], v[98:113]
	v_mfma_f32_32x32x16_bf16 v[66:81], v[236:239], v[146:149], v[66:81]
	v_mfma_f32_32x32x16_bf16 v[98:113], v[240:243], v[134:137], v[98:113]
	v_mfma_f32_32x32x16_bf16 v[66:81], v[240:243], v[150:153], v[66:81]
	v_mfma_f32_32x32x16_bf16 v[98:113], v[244:247], v[138:141], v[98:113]
	v_mfma_f32_32x32x16_bf16 v[66:81], v[244:247], v[154:157], v[66:81]
	v_mfma_f32_32x32x16_bf16 v[98:113], v[248:251], v[142:145], v[98:113]
	v_mfma_f32_32x32x16_bf16 v[66:81], v[248:251], v[158:161], v[66:81]
	s_setprio 0
	s_barrier
	ds_read_b128 v[130:133], v192 offset:8192
	ds_read_b128 v[134:137], v193 offset:8192
	ds_read_b128 v[138:141], v194 offset:8192
	ds_read_b128 v[142:145], v195 offset:8192
	ds_read_b128 v[146:149], v192 offset:12288
	ds_read_b128 v[150:153], v193 offset:12288
	ds_read_b128 v[154:157], v194 offset:12288
	ds_read_b128 v[158:161], v195 offset:12288
	s_waitcnt vmcnt(4)
	s_barrier
	s_waitcnt lgkmcnt(0)
	s_setprio 1
	v_mfma_f32_32x32x16_bf16 v[50:65], v[196:199], v[130:133], v[50:65]
	v_mfma_f32_32x32x16_bf16 v[18:33], v[196:199], v[146:149], v[18:33]
	v_mfma_f32_32x32x16_bf16 v[50:65], v[208:211], v[134:137], v[50:65]
	v_mfma_f32_32x32x16_bf16 v[18:33], v[208:211], v[150:153], v[18:33]
	v_mfma_f32_32x32x16_bf16 v[50:65], v[218:221], v[138:141], v[50:65]
	v_mfma_f32_32x32x16_bf16 v[18:33], v[218:221], v[154:157], v[18:33]
	v_mfma_f32_32x32x16_bf16 v[50:65], v[222:225], v[142:145], v[50:65]
	v_mfma_f32_32x32x16_bf16 v[18:33], v[222:225], v[158:161], v[18:33]
	s_setprio 0
	s_setprio 1
	v_mfma_f32_32x32x16_bf16 v[34:49], v[236:239], v[130:133], v[34:49]
	v_mfma_f32_32x32x16_bf16 v[2:17], v[236:239], v[146:149], v[2:17]
	v_mfma_f32_32x32x16_bf16 v[34:49], v[240:243], v[134:137], v[34:49]
	v_mfma_f32_32x32x16_bf16 v[2:17], v[240:243], v[150:153], v[2:17]
	v_mfma_f32_32x32x16_bf16 v[34:49], v[244:247], v[138:141], v[34:49]
	v_mfma_f32_32x32x16_bf16 v[2:17], v[244:247], v[154:157], v[2:17]
	v_mfma_f32_32x32x16_bf16 v[34:49], v[248:251], v[142:145], v[34:49]
	v_mfma_f32_32x32x16_bf16 v[2:17], v[248:251], v[158:161], v[2:17]
	s_setprio 0
	s_barrier
	ds_read_b128 v[196:199], v203 offset:32768
	ds_read_b128 v[208:211], v204 offset:32768
	ds_read_b128 v[218:221], v214 offset:32768
	ds_read_b128 v[222:225], v226 offset:32768
	ds_read_b128 v[130:133], v192 offset:32768
	ds_read_b128 v[134:137], v193 offset:32768
	ds_read_b128 v[138:141], v194 offset:32768
	ds_read_b128 v[142:145], v195 offset:32768
	ds_read_b128 v[146:149], v192 offset:36864
	ds_read_b128 v[150:153], v193 offset:36864
	ds_read_b128 v[154:157], v194 offset:36864
	ds_read_b128 v[158:161], v195 offset:36864
	s_waitcnt vmcnt(2)
	s_barrier
	s_waitcnt lgkmcnt(0)
	s_setprio 1
	v_mfma_f32_32x32x16_bf16 v[114:129], v[196:199], v[130:133], v[114:129]
	v_mfma_f32_32x32x16_bf16 v[82:97], v[196:199], v[146:149], v[82:97]
	v_mfma_f32_32x32x16_bf16 v[114:129], v[208:211], v[134:137], v[114:129]
	v_mfma_f32_32x32x16_bf16 v[82:97], v[208:211], v[150:153], v[82:97]
	v_mfma_f32_32x32x16_bf16 v[114:129], v[218:221], v[138:141], v[114:129]
	v_mfma_f32_32x32x16_bf16 v[82:97], v[218:221], v[154:157], v[82:97]
	v_mfma_f32_32x32x16_bf16 v[114:129], v[222:225], v[142:145], v[114:129]
	v_mfma_f32_32x32x16_bf16 v[82:97], v[222:225], v[158:161], v[82:97]
	s_setprio 0
	s_barrier
	ds_read_b128 v[236:239], v203 offset:36864
	ds_read_b128 v[240:243], v204 offset:36864
	ds_read_b128 v[244:247], v214 offset:36864
	ds_read_b128 v[248:251], v226 offset:36864
	s_waitcnt vmcnt(0)
	s_barrier
	s_waitcnt lgkmcnt(0)
	s_setprio 1
	v_mfma_f32_32x32x16_bf16 v[98:113], v[236:239], v[130:133], v[98:113]
	v_mfma_f32_32x32x16_bf16 v[66:81], v[236:239], v[146:149], v[66:81]
	v_mfma_f32_32x32x16_bf16 v[98:113], v[240:243], v[134:137], v[98:113]
	v_mfma_f32_32x32x16_bf16 v[66:81], v[240:243], v[150:153], v[66:81]
	v_mfma_f32_32x32x16_bf16 v[98:113], v[244:247], v[138:141], v[98:113]
	v_mfma_f32_32x32x16_bf16 v[66:81], v[244:247], v[154:157], v[66:81]
	v_mfma_f32_32x32x16_bf16 v[98:113], v[248:251], v[142:145], v[98:113]
	v_mfma_f32_32x32x16_bf16 v[66:81], v[248:251], v[158:161], v[66:81]
	s_setprio 0
	s_barrier
	ds_read_b128 v[130:133], v192 offset:40960
	ds_read_b128 v[134:137], v193 offset:40960
	ds_read_b128 v[138:141], v194 offset:40960
	ds_read_b128 v[142:145], v195 offset:40960
	ds_read_b128 v[146:149], v192 offset:45056
	ds_read_b128 v[150:153], v193 offset:45056
	ds_read_b128 v[154:157], v194 offset:45056
	ds_read_b128 v[158:161], v195 offset:45056
	s_barrier
	s_waitcnt lgkmcnt(0)
	s_setprio 1
	v_mfma_f32_32x32x16_bf16 v[50:65], v[196:199], v[130:133], v[50:65]
	v_mfma_f32_32x32x16_bf16 v[18:33], v[196:199], v[146:149], v[18:33]
	v_mfma_f32_32x32x16_bf16 v[50:65], v[208:211], v[134:137], v[50:65]
	v_mfma_f32_32x32x16_bf16 v[18:33], v[208:211], v[150:153], v[18:33]
	v_mfma_f32_32x32x16_bf16 v[50:65], v[218:221], v[138:141], v[50:65]
	v_mfma_f32_32x32x16_bf16 v[18:33], v[218:221], v[154:157], v[18:33]
	v_mfma_f32_32x32x16_bf16 v[50:65], v[222:225], v[142:145], v[50:65]
	v_mfma_f32_32x32x16_bf16 v[18:33], v[222:225], v[158:161], v[18:33]
	s_setprio 0
	s_setprio 1
	v_mfma_f32_32x32x16_bf16 v[34:49], v[236:239], v[130:133], v[34:49]
	v_mfma_f32_32x32x16_bf16 v[2:17], v[236:239], v[146:149], v[2:17]
	v_mfma_f32_32x32x16_bf16 v[34:49], v[240:243], v[134:137], v[34:49]
	v_mfma_f32_32x32x16_bf16 v[2:17], v[240:243], v[150:153], v[2:17]
	v_mfma_f32_32x32x16_bf16 v[34:49], v[244:247], v[138:141], v[34:49]
	v_mfma_f32_32x32x16_bf16 v[2:17], v[244:247], v[154:157], v[2:17]
	v_mfma_f32_32x32x16_bf16 v[34:49], v[248:251], v[142:145], v[34:49]
	v_mfma_f32_32x32x16_bf16 v[2:17], v[248:251], v[158:161], v[2:17]
	s_setprio 0
	s_barrier
	v_readfirstlane_b32 s42, v200
	s_lshr_b32 s42, s42, 8
	s_cmp_lg_u32 s42, 0
	s_cbranch_scc1 .Lgin_nolag2
	s_barrier
.Lgin_nolag2:
	s_nop 15
	s_nop 15
	s_waitcnt lgkmcnt(3)
	s_waitcnt lgkmcnt(2)
	s_waitcnt lgkmcnt(1)
	s_waitcnt lgkmcnt(0)
	s_waitcnt lgkmcnt(0)
	v_add_u32_e32 v0, 0x12000, v172
	v_add_u32_e32 v0, 0x14400, v172
	v_add_u32_e32 v0, 0x16800, v172
	v_add_u32_e32 v0, 0x18c00, v172
	s_waitcnt lgkmcnt(3)
	s_waitcnt lgkmcnt(2)
	s_waitcnt lgkmcnt(1)
	s_waitcnt lgkmcnt(0)
	s_waitcnt lgkmcnt(0)
	v_add_u32_e32 v0, 0x1b000, v172
	v_add_u32_e32 v0, 0x1d400, v172
	v_add_u32_e32 v0, 0x1f800, v172
	v_add_u32_e32 v0, 0x21c00, v172
	s_waitcnt lgkmcnt(3)
	s_waitcnt lgkmcnt(2)
	s_waitcnt lgkmcnt(1)
	s_waitcnt lgkmcnt(0)
	s_waitcnt lgkmcnt(0)
	v_add_u32_e32 v0, 0x12000, v170
	s_waitcnt lgkmcnt(3)
	s_waitcnt lgkmcnt(2)
	s_waitcnt lgkmcnt(1)
	s_waitcnt lgkmcnt(0)
	s_waitcnt lgkmcnt(0)
	s_waitcnt lgkmcnt(1)
	s_waitcnt lgkmcnt(0)
	s_waitcnt lgkmcnt(0)
	s_waitcnt lgkmcnt(3)
	s_waitcnt lgkmcnt(2)
	s_waitcnt lgkmcnt(1)
	s_waitcnt lgkmcnt(0)
	s_waitcnt lgkmcnt(0)
	s_waitcnt lgkmcnt(3)
	s_waitcnt lgkmcnt(2)
	s_waitcnt lgkmcnt(1)
	s_waitcnt lgkmcnt(0)
	s_waitcnt lgkmcnt(0)
	s_waitcnt lgkmcnt(4)
	v_add_u32_e32 v147, s1, v233
	s_movk_i32 s1, 0x4000
	s_waitcnt lgkmcnt(0)
	v_or_b32_e32 v132, v147, v177
	v_cmp_gt_i32_e64 s[44:45], s1, v132
	v_cmp_lt_i32_e32 vcc, s24, v132
	s_and_saveexec_b64 s[2:3], vcc
	s_xor_b64 s[2:3], exec, s[2:3]
	v_add_u32_e32 v0, 0xffffc000, v147
	v_lshrrev_b32_e32 v142, 8, v0
	v_and_b32_e32 v0, 0x9f, v132
	v_or_b32_e32 v0, 0x2000, v0
	s_or_saveexec_b64 s[2:3], s[2:3]
	v_lshrrev_b32_e32 v130, 2, v147
	v_mov_b32_e32 v131, 0
	v_ashrrev_i32_e32 v146, 13, v147
	v_and_b32_e32 v148, 0x7e0, v130
	v_mov_b32_e32 v160, 0
	s_xor_b64 exec, exec, s[2:3]
	v_ashrrev_i32_e32 v142, 13, v147
	v_and_b32_e32 v0, 0x1f9f, v132
	v_and_b32_e32 v131, 0x7e0, v130
	v_mov_b32_e32 v160, v175
	s_or_b64 exec, exec, s[2:3]
	v_lshlrev_b32_e32 v134, 1, v0
	v_lshrrev_b32_e32 v135, 1, v0
	v_and_b32_e32 v133, 0x3ff3, v0
	v_and_b32_e32 v134, 8, v134
	v_and_b32_e32 v135, 4, v135
	v_and_b32_e32 v130, 0xc0, v231
	v_or3_b32 v140, v134, v133, v135
	v_ashrrev_i32_e32 v133, 31, v132
	v_or_b32_e32 v130, s0, v130
	v_lshlrev_b64 v[134:135], 8, v[132:133]
	v_lshl_add_u64 v[138:139], s[36:37], 0, v[134:135]
	v_lshlrev_b64 v[134:135], 3, v[132:133]
	v_lshlrev_b64 v[136:137], 9, v[132:133]
	v_lshlrev_b32_e32 v144, 1, v140
	v_mov_b32_e32 v145, v1
	v_ashrrev_i32_e32 v133, 5, v130
	v_or_b32_e32 v158, v131, v174
	v_or_b32_e32 v159, v131, v173
	v_or_b32_e32 v156, v131, v234
	v_or_b32_e32 v157, v131, v235
	v_or_b32_e32 v154, v160, v174
	v_or_b32_e32 v155, v160, v173
	v_or_b32_e32 v152, v160, v234
	v_or_b32_e32 v153, v160, v235
	v_mul_lo_u32 v150, v142, 6
	v_lshl_add_u64 v[136:137], v[178:179], 0, v[136:137]
	v_lshlrev_b32_e32 v149, 2, v142
	v_lshl_add_u64 v[140:141], v[180:181], 0, v[144:145]
	v_lshlrev_b32_e32 v151, 1, v142
	v_lshl_add_u64 v[142:143], v[182:183], 0, v[144:145]
	v_cmp_lt_i32_e64 s[42:43], 15, v133
	s_and_saveexec_b64 s[0:1], s[42:43]
	s_xor_b64 s[2:3], exec, s[0:1]
	s_cbranch_execz .LBB0_257
	v_cmp_lt_u32_e32 vcc, 19, v133
	s_and_saveexec_b64 s[0:1], vcc
	s_xor_b64 s[40:41], exec, s[0:1]
	s_cbranch_execz .LBB0_254
	v_cmp_lt_u32_e32 vcc, 35, v133
	s_and_saveexec_b64 s[0:1], vcc
	s_xor_b64 s[22:23], exec, s[0:1]
	s_cbranch_execz .LBB0_245
	v_cmp_lt_u32_e32 vcc, 43, v133
	s_and_saveexec_b64 s[0:1], vcc
	s_xor_b64 s[88:89], exec, s[0:1]
	s_cbranch_execz .LBB0_242
	v_cmp_lt_u32_e32 vcc, 55, v133
	s_and_saveexec_b64 s[0:1], vcc
	s_xor_b64 s[90:91], exec, s[0:1]
	s_cbranch_execz .LBB0_231
	s_movk_i32 s0, 0x700
	v_cmp_eq_u32_e32 vcc, s0, v130
	s_and_saveexec_b64 s[92:93], vcc
	s_cbranch_execz .LBB0_230
	s_and_saveexec_b64 s[94:95], s[44:45]
	s_cbranch_execz .LBB0_229
	v_lshlrev_b32_e32 v131, 3, v158
	v_lshlrev_b32_e32 v161, 3, v159
	global_load_dwordx2 v[144:145], v131, s[80:81]
	global_load_dwordx2 v[196:197], v161, s[80:81]
	v_lshlrev_b32_e32 v131, 3, v157
	s_waitcnt vmcnt(1)
	v_mov_b32_e32 v198, v144
	s_waitcnt vmcnt(0)
	v_mov_b32_e32 v199, v196
	v_mov_b32_e32 v196, v145
	v_pk_mul_f32 v[144:145], v[122:123], v[196:197]
	s_nop 0
	v_pk_fma_f32 v[144:145], v[114:115], v[198:199], v[144:145] neg_lo:[0,0,1] neg_hi:[0,0,1]
	v_pk_mul_f32 v[114:115], v[114:115], v[196:197]
	s_nop 0
	v_pk_fma_f32 v[122:123], v[122:123], v[198:199], v[114:115]
	v_lshlrev_b32_e32 v114, 3, v156
	global_load_dwordx2 v[114:115], v114, s[80:81]
	s_nop 0
	global_load_dwordx2 v[196:197], v131, s[80:81]
	s_waitcnt vmcnt(1)
	v_mov_b32_e32 v198, v114
	s_waitcnt vmcnt(0)
	v_mov_b32_e32 v199, v196
	v_mov_b32_e32 v196, v115
	v_pk_mul_f32 v[114:115], v[124:125], v[196:197]
	s_nop 0
	v_pk_fma_f32 v[208:209], v[116:117], v[198:199], v[114:115] neg_lo:[0,0,1] neg_hi:[0,0,1]
	v_pk_mul_f32 v[114:115], v[116:117], v[196:197]
	v_lshlrev_b32_e32 v116, 3, v155
	v_pk_fma_f32 v[124:125], v[124:125], v[198:199], v[114:115]
	v_lshlrev_b32_e32 v114, 3, v154
	global_load_dwordx2 v[114:115], v114, s[80:81]
	s_nop 0
	global_load_dwordx2 v[116:117], v116, s[80:81]
	s_waitcnt vmcnt(1)
	v_mov_b32_e32 v196, v114
	s_waitcnt vmcnt(0)
	v_mov_b32_e32 v197, v116
	v_mov_b32_e32 v116, v115
	v_pk_mul_f32 v[114:115], v[126:127], v[116:117]
	s_nop 0
	v_pk_fma_f32 v[198:199], v[118:119], v[196:197], v[114:115] neg_lo:[0,0,1] neg_hi:[0,0,1]
	v_pk_mul_f32 v[114:115], v[118:119], v[116:117]
	v_lshlrev_b32_e32 v116, 3, v152
	v_pk_fma_f32 v[126:127], v[126:127], v[196:197], v[114:115]
	v_lshlrev_b32_e32 v114, 3, v153
	global_load_dwordx2 v[114:115], v114, s[80:81]
	s_nop 0
	global_load_dwordx2 v[116:117], v116, s[80:81]
	s_waitcnt vmcnt(1)
	v_mov_b32_e32 v197, v115
	s_waitcnt vmcnt(0)
	v_mov_b32_e32 v196, v117
	v_mov_b32_e32 v118, v116
	v_mov_b32_e32 v119, v114
	v_pk_mul_f32 v[196:197], v[128:129], v[196:197]
	v_mul_f32_e32 v116, v128, v116
	v_pk_fma_f32 v[196:197], v[120:121], v[118:119], v[196:197] neg_lo:[0,0,1] neg_hi:[0,0,1]
	v_mul_f32_e32 v118, v120, v117
	v_mov_b32_e32 v120, v129
	v_pk_mul_f32 v[114:115], v[120:121], v[114:115]
	v_mov_b32_e32 v120, v196
	v_mov_b32_e32 v117, v114
	v_mov_b32_e32 v119, v115
	v_pk_add_f32 v[128:129], v[116:117], v[118:119]
	v_mov_b32_e32 v114, v144
	v_mov_b32_e32 v115, v145
	v_mov_b32_e32 v116, v208
	v_mov_b32_e32 v117, v209
	v_mov_b32_e32 v118, v198
	v_mov_b32_e32 v119, v199
	v_mov_b32_e32 v121, v197
